# forget-gate tile epilogue reads the lower bounds from LDS (filled once per tile) instead of per-chunk global loads behind vmcnt waits
# baseline (speedup 1.0000x reference)
.LBB0_269:
	s_cmp_lg_u32 s49, 4
	s_cbranch_scc1 .Llb_skip
	v_bfe_u32 v128, v184, 6, 2
	v_bfe_u32 v129, v184, 4, 2
	v_lshlrev_b32_e32 v128, 7, v128
	v_lshl_add_u32 v128, v129, 5, v128
	v_lshlrev_b32_e32 v130, 2, v184
	v_sub_u32_e32 v128, v130, v128
	v_ashrrev_i32_e32 v129, 31, v128
	v_lshl_add_u64 v[128:129], v[148:149], 0, v[128:129]
	global_load_dword v131, v[128:129], off
	v_add_u32_e32 v130, 0x21800, v130
	s_waitcnt vmcnt(0)
	ds_write_b32 v130, v131
	s_waitcnt lgkmcnt(0)
	s_barrier

.LBB0_288:
	s_andn2_b64 vcc, exec, s[34:35]
	s_cbranch_vccnz .LBB0_290
	v_mul_f32_e32 v128, 0xbfb8aa3b, v182
	v_exp_f32_e32 v128, v128
	v_mul_f32_e32 v161, 0x3fb8aa3b, v203
	v_exp_f32_e32 v161, v161
	v_add_f32_e32 v128, 1.0, v128
	v_rcp_f32_e32 v157, v128
	v_mul_f32_e32 v128, 0x3fb8aa3b, v182
	v_exp_f32_e32 v128, v128
	v_add_f32_e32 v161, 1.0, v161
	v_rcp_f32_e32 v211, v161
	v_mul_f32_e32 v161, 0x3fb8aa3b, v181
	v_add_f32_e32 v128, 1.0, v128
	v_rcp_f32_e32 v206, v128
	v_mul_f32_e32 v128, 0xbfb8aa3b, v183
	v_exp_f32_e32 v128, v128
	v_exp_f32_e32 v161, v161
	v_add_f32_e32 v128, 1.0, v128
	v_rcp_f32_e32 v159, v128
	v_mul_f32_e32 v128, 0x3fb8aa3b, v183
	v_exp_f32_e32 v128, v128
	v_add_f32_e32 v161, 1.0, v161
	v_rcp_f32_e32 v215, v161
	v_add_f32_e32 v128, 1.0, v128
	v_rcp_f32_e32 v207, v128
	v_bfe_u32 v132, v184, 6, 2
	v_bfe_u32 v133, v184, 4, 2
	v_lshlrev_b32_e32 v132, 7, v132
	v_lshl_add_u32 v132, v133, 5, v132
	v_add_u32_e32 v132, 0x21800, v132
	ds_read_b128 v[128:131], v132 offset:16
	ds_read_b128 v[132:135], v132
	s_waitcnt lgkmcnt(1)
	v_pk_add_f32 v[222:223], v[128:129], 1.0 op_sel_hi:[1,0] neg_lo:[1,0] neg_hi:[1,0]
	s_waitcnt lgkmcnt(0)
	v_pk_add_f32 v[208:209], v[132:133], 1.0 op_sel_hi:[1,0] neg_lo:[1,0] neg_hi:[1,0]
	v_pk_add_f32 v[212:213], v[134:135], 1.0 op_sel_hi:[1,0] neg_lo:[1,0] neg_hi:[1,0]
	v_fma_f32 v132, v157, v208, v132
	v_max_f32_e32 v132, 0xda24260, v132
	v_cmp_gt_f32_e32 vcc, s93, v132
	v_fma_f32 v133, v159, v209, v133
	v_max_f32_e32 v133, 0xda24260, v133
	v_cndmask_b32_e64 v157, 0, 32, vcc
	v_ldexp_f32 v132, v132, v157
	v_log_f32_e32 v132, v132
	v_mul_f32_e32 v159, 0x3fb8aa3b, v202
	v_exp_f32_e32 v159, v159
	v_pk_add_f32 v[230:231], v[130:131], 1.0 op_sel_hi:[1,0] neg_lo:[1,0] neg_hi:[1,0]
	v_mul_f32_e32 v157, 0x3f317217, v132
	v_fma_f32 v157, v132, s95, -v157
	v_fmac_f32_e32 v157, 0x3377d1cf, v132
	v_fmac_f32_e32 v157, 0x3f317217, v132
	v_cmp_lt_f32_e64 s[42:43], |v132|, s62
	v_add_f32_e32 v159, 1.0, v159
	v_rcp_f32_e32 v210, v159
	v_cndmask_b32_e64 v132, v132, v157, s[42:43]
	v_cndmask_b32_e32 v157, 0, v225, vcc
	v_cmp_gt_f32_e32 vcc, s93, v133
	v_sub_f32_e32 v132, v132, v157
	v_mul_f32_e32 v159, 0xbfb8aa3b, v203
	v_cndmask_b32_e64 v157, 0, 32, vcc
	v_ldexp_f32 v133, v133, v157
	v_log_f32_e32 v133, v133
	v_exp_f32_e32 v159, v159
	v_pk_mul_f32 v[208:209], v[206:207], v[208:209]
	v_pk_mul_f32 v[206:207], v[210:211], v[212:213]
	v_mul_f32_e32 v157, 0x3f317217, v133
	v_fma_f32 v157, v133, s95, -v157
	v_fmac_f32_e32 v157, 0x3377d1cf, v133
	v_fmac_f32_e32 v157, 0x3f317217, v133
	v_cmp_lt_f32_e64 s[42:43], |v133|, s62
	v_add_f32_e32 v159, 1.0, v159
	v_rcp_f32_e32 v159, v159
	v_cndmask_b32_e64 v133, v133, v157, s[42:43]
	v_cndmask_b32_e32 v157, 0, v225, vcc
	v_sub_f32_e32 v133, v133, v157
	v_mul_f32_e32 v157, 0xbfb8aa3b, v202
	v_exp_f32_e32 v157, v157
	v_fmac_f32_e32 v135, v159, v213
	v_max_f32_e32 v135, 0xda24260, v135
	v_mul_f32_e32 v159, 0x3fb8aa3b, v180
	v_add_f32_e32 v157, 1.0, v157
	v_rcp_f32_e32 v157, v157
	v_exp_f32_e32 v159, v159
	v_lshl_add_u64 v[210:211], v[146:147], 0, v[178:179]
	v_fma_f32 v134, v157, v212, v134
	v_max_f32_e32 v134, 0xda24260, v134
	v_cmp_gt_f32_e32 vcc, s93, v134
	v_add_f32_e32 v159, 1.0, v159
	v_rcp_f32_e32 v214, v159
	v_cndmask_b32_e64 v157, 0, 32, vcc
	v_ldexp_f32 v134, v134, v157
	v_log_f32_e32 v134, v134
	v_mul_f32_e32 v159, 0xbfb8aa3b, v181
	v_exp_f32_e32 v159, v159
	v_mul_f32_e32 v157, 0x3f317217, v134
	v_fma_f32 v157, v134, s95, -v157
	v_fmac_f32_e32 v157, 0x3377d1cf, v134
	v_fmac_f32_e32 v157, 0x3f317217, v134
	v_cmp_lt_f32_e64 s[42:43], |v134|, s62
	v_add_f32_e32 v159, 1.0, v159
	v_rcp_f32_e32 v159, v159
	v_cndmask_b32_e64 v134, v134, v157, s[42:43]
	v_cndmask_b32_e32 v157, 0, v225, vcc
	v_cmp_gt_f32_e32 vcc, s93, v135
	v_sub_f32_e32 v134, v134, v157
	s_nop 0
	v_cndmask_b32_e64 v157, 0, 32, vcc
	v_ldexp_f32 v135, v135, v157
	v_log_f32_e32 v135, v135
	s_nop 0
	v_mul_f32_e32 v157, 0x3f317217, v135
	v_fma_f32 v157, v135, s95, -v157
	v_fmac_f32_e32 v157, 0x3377d1cf, v135
	v_fmac_f32_e32 v157, 0x3f317217, v135
	v_cmp_lt_f32_e64 s[42:43], |v135|, s62
	s_nop 1
	v_cndmask_b32_e64 v135, v135, v157, s[42:43]
	v_cndmask_b32_e32 v157, 0, v225, vcc
	v_sub_f32_e32 v135, v135, v157
	v_mul_f32_e32 v157, 0xbfb8aa3b, v180
	v_exp_f32_e32 v157, v157
	s_nop 0
	v_add_f32_e32 v157, 1.0, v157
	v_rcp_f32_e32 v157, v157
	s_nop 0
	v_fma_f32 v128, v157, v222, v128
	v_max_f32_e32 v128, 0xda24260, v128
	v_cmp_gt_f32_e32 vcc, s93, v128
	s_nop 1
	v_cndmask_b32_e64 v157, 0, 32, vcc
	v_ldexp_f32 v128, v128, v157
	v_log_f32_e32 v128, v128
	s_nop 0
	v_mul_f32_e32 v157, 0x3f317217, v128
	v_fma_f32 v157, v128, s95, -v157
	v_fmac_f32_e32 v157, 0x3377d1cf, v128
	v_fmac_f32_e32 v157, 0x3f317217, v128
	v_cmp_lt_f32_e64 s[42:43], |v128|, s62
	s_nop 1
	v_cndmask_b32_e64 v128, v128, v157, s[42:43]
	v_cndmask_b32_e32 v157, 0, v225, vcc
	v_sub_f32_e32 v218, v128, v157
	v_fma_f32 v128, v159, v223, v129
	v_max_f32_e32 v128, 0xda24260, v128
	v_cmp_gt_f32_e32 vcc, s93, v128
	s_nop 1
	v_cndmask_b32_e64 v129, 0, 32, vcc
	v_ldexp_f32 v128, v128, v129
	v_log_f32_e32 v128, v128
	s_nop 0
	v_mul_f32_e32 v129, 0x3f317217, v128
	v_fma_f32 v129, v128, s95, -v129
	v_fmac_f32_e32 v129, 0x3377d1cf, v128
	v_fmac_f32_e32 v129, 0x3f317217, v128
	v_cmp_lt_f32_e64 s[42:43], |v128|, s62
	s_nop 1
	v_cndmask_b32_e64 v128, v128, v129, s[42:43]
	v_cndmask_b32_e32 v129, 0, v225, vcc
	v_sub_f32_e32 v219, v128, v129
	v_mul_f32_e32 v128, 0xbfb8aa3b, v204
	v_exp_f32_e32 v128, v128
	v_mul_f32_e32 v129, 0xbfb8aa3b, v205
	v_exp_f32_e32 v129, v129
	v_add_f32_e32 v128, 1.0, v128
	v_rcp_f32_e32 v157, v128
	v_add_f32_e32 v129, 1.0, v129
	v_rcp_f32_e32 v159, v129
	v_mul_f32_e32 v128, 0x3fb8aa3b, v204
	v_fma_f32 v130, v157, v230, v130
	v_max_f32_e32 v130, 0xda24260, v130
	v_cmp_gt_f32_e32 vcc, s93, v130
	v_fmac_f32_e32 v131, v159, v231
	v_mul_f32_e32 v129, 0x3fb8aa3b, v205
	v_cndmask_b32_e64 v157, 0, 32, vcc
	v_ldexp_f32 v130, v130, v157
	v_log_f32_e32 v130, v130
	v_exp_f32_e32 v128, v128
	v_exp_f32_e32 v129, v129
	v_mul_f32_e32 v157, 0x3f317217, v130
	v_fma_f32 v157, v130, s95, -v157
	v_fmac_f32_e32 v157, 0x3377d1cf, v130
	v_fmac_f32_e32 v157, 0x3f317217, v130
	v_cmp_lt_f32_e64 s[42:43], |v130|, s62
	v_add_f32_e32 v128, 1.0, v128
	v_add_f32_e32 v129, 1.0, v129
	v_cndmask_b32_e64 v130, v130, v157, s[42:43]
	v_cndmask_b32_e32 v157, 0, v225, vcc
	v_sub_f32_e32 v220, v130, v157
	v_max_f32_e32 v130, 0xda24260, v131
	v_cmp_gt_f32_e32 vcc, s93, v130
	v_rcp_f32_e32 v128, v128
	v_rcp_f32_e32 v129, v129
	v_cndmask_b32_e64 v131, 0, 32, vcc
	v_ldexp_f32 v130, v130, v131
	v_log_f32_e32 v130, v130
	v_pk_mul_f32 v[128:129], v[128:129], v[230:231]
	v_mul_f32_e32 v131, 0x3f317217, v130
	v_fma_f32 v131, v130, s95, -v131
	v_fmac_f32_e32 v131, 0x3377d1cf, v130
	v_fmac_f32_e32 v131, 0x3f317217, v130
	v_cmp_lt_f32_e64 s[42:43], |v130|, s62
	s_nop 1
	v_cndmask_b32_e64 v130, v130, v131, s[42:43]
	v_cndmask_b32_e32 v131, 0, v225, vcc
	v_sub_f32_e32 v221, v130, v131
	v_pk_mul_f32 v[130:131], v[214:215], v[222:223]
	global_store_dwordx4 v[210:211], v[132:135], off
	global_store_dwordx4 v[210:211], v[218:221], off offset:16

.LBB0_300:
	s_andn2_b64 vcc, exec, s[36:37]
	s_cbranch_vccnz .LBB0_302
	v_bfe_u32 v124, v184, 6, 2
	v_bfe_u32 v125, v184, 4, 2
	v_lshlrev_b32_e32 v124, 7, v124
	v_lshl_add_u32 v124, v125, 5, v124
	v_add_u32_e32 v124, 0x21800, v124
	ds_read_b128 v[120:123], v124 offset:528
	ds_read_b128 v[124:127], v124 offset:512
	v_mul_f32_e32 v157, 0xbfb8aa3b, v132
	v_exp_f32_e32 v157, v157
	v_mul_f32_e32 v159, 0x3fb8aa3b, v132
	v_exp_f32_e32 v159, v159
	v_mul_f32_e32 v161, 0x3fb8aa3b, v133
	v_add_f32_e32 v157, 1.0, v157
	v_rcp_f32_e32 v157, v157
	v_add_f32_e32 v159, 1.0, v159
	v_rcp_f32_e32 v182, v159
	v_mul_f32_e32 v159, 0xbfb8aa3b, v133
	v_exp_f32_e32 v159, v159
	v_exp_f32_e32 v161, v161
	v_lshl_add_u64 v[178:179], v[150:151], 0, v[178:179]
	v_add_f32_e32 v159, 1.0, v159
	v_rcp_f32_e32 v159, v159
	v_add_f32_e32 v161, 1.0, v161
	v_rcp_f32_e32 v183, v161
	v_mul_f32_e32 v161, 0x3fb8aa3b, v135
	v_exp_f32_e32 v161, v161
	s_waitcnt lgkmcnt(1)
	v_pk_add_f32 v[214:215], v[120:121], 1.0 op_sel_hi:[1,0] neg_lo:[1,0] neg_hi:[1,0]
	s_waitcnt lgkmcnt(0)
	v_pk_add_f32 v[202:203], v[124:125], 1.0 op_sel_hi:[1,0] neg_lo:[1,0] neg_hi:[1,0]
	v_pk_add_f32 v[206:207], v[126:127], 1.0 op_sel_hi:[1,0] neg_lo:[1,0] neg_hi:[1,0]
	v_fma_f32 v124, v157, v202, v124
	v_max_f32_e32 v124, 0xda24260, v124
	v_cmp_gt_f32_e32 vcc, s93, v124
	v_fma_f32 v125, v159, v203, v125
	v_max_f32_e32 v125, 0xda24260, v125
	v_cndmask_b32_e64 v157, 0, 32, vcc
	v_ldexp_f32 v124, v124, v157
	v_log_f32_e32 v124, v124
	v_mul_f32_e32 v159, 0x3fb8aa3b, v134
	v_exp_f32_e32 v159, v159
	v_pk_add_f32 v[218:219], v[122:123], 1.0 op_sel_hi:[1,0] neg_lo:[1,0] neg_hi:[1,0]
	v_mul_f32_e32 v157, 0x3f317217, v124
	v_fma_f32 v157, v124, s95, -v157
	v_fmac_f32_e32 v157, 0x3377d1cf, v124
	v_fmac_f32_e32 v157, 0x3f317217, v124
	v_cmp_lt_f32_e64 s[46:47], |v124|, s62
	v_add_f32_e32 v159, 1.0, v159
	v_rcp_f32_e32 v204, v159
	v_cndmask_b32_e64 v124, v124, v157, s[46:47]
	v_cndmask_b32_e32 v157, 0, v225, vcc
	v_cmp_gt_f32_e32 vcc, s93, v125
	v_sub_f32_e32 v124, v124, v157
	v_mul_f32_e32 v159, 0xbfb8aa3b, v135
	v_cndmask_b32_e64 v157, 0, 32, vcc
	v_ldexp_f32 v125, v125, v157
	v_log_f32_e32 v125, v125
	v_exp_f32_e32 v159, v159
	v_add_f32_e32 v161, 1.0, v161
	v_rcp_f32_e32 v205, v161
	v_mul_f32_e32 v157, 0x3f317217, v125
	v_fma_f32 v157, v125, s95, -v157
	v_fmac_f32_e32 v157, 0x3377d1cf, v125
	v_fmac_f32_e32 v157, 0x3f317217, v125
	v_cmp_lt_f32_e64 s[46:47], |v125|, s62
	v_add_f32_e32 v159, 1.0, v159
	v_rcp_f32_e32 v159, v159
	v_cndmask_b32_e64 v125, v125, v157, s[46:47]
	v_cndmask_b32_e32 v157, 0, v225, vcc
	v_sub_f32_e32 v125, v125, v157
	v_mul_f32_e32 v157, 0xbfb8aa3b, v134
	v_exp_f32_e32 v157, v157
	v_fmac_f32_e32 v127, v159, v207
	v_max_f32_e32 v127, 0xda24260, v127
	v_mul_f32_e32 v159, 0x3fb8aa3b, v130
	v_add_f32_e32 v157, 1.0, v157
	v_rcp_f32_e32 v157, v157
	v_exp_f32_e32 v159, v159
	v_mul_f32_e32 v161, 0x3fb8aa3b, v131
	v_exp_f32_e32 v161, v161
	v_fma_f32 v126, v157, v206, v126
	v_max_f32_e32 v126, 0xda24260, v126
	v_cmp_gt_f32_e32 vcc, s93, v126
	v_add_f32_e32 v159, 1.0, v159
	v_rcp_f32_e32 v208, v159
	v_cndmask_b32_e64 v157, 0, 32, vcc
	v_ldexp_f32 v126, v126, v157
	v_log_f32_e32 v126, v126
	v_mul_f32_e32 v159, 0xbfb8aa3b, v131
	v_exp_f32_e32 v159, v159
	v_add_f32_e32 v161, 1.0, v161
	v_mul_f32_e32 v157, 0x3f317217, v126
	v_fma_f32 v157, v126, s95, -v157
	v_fmac_f32_e32 v157, 0x3377d1cf, v126
	v_fmac_f32_e32 v157, 0x3f317217, v126
	v_cmp_lt_f32_e64 s[46:47], |v126|, s62
	v_add_f32_e32 v159, 1.0, v159
	v_rcp_f32_e32 v159, v159
	v_cndmask_b32_e64 v126, v126, v157, s[46:47]
	v_cndmask_b32_e32 v157, 0, v225, vcc
	v_cmp_gt_f32_e32 vcc, s93, v127
	v_sub_f32_e32 v126, v126, v157
	v_rcp_f32_e32 v209, v161
	v_cndmask_b32_e64 v157, 0, 32, vcc
	v_ldexp_f32 v127, v127, v157
	v_log_f32_e32 v127, v127
	v_pk_mul_f32 v[202:203], v[182:183], v[202:203]
	v_pk_mul_f32 v[182:183], v[204:205], v[206:207]
	v_mul_f32_e32 v157, 0x3f317217, v127
	v_fma_f32 v157, v127, s95, -v157
	v_fmac_f32_e32 v157, 0x3377d1cf, v127
	v_fmac_f32_e32 v157, 0x3f317217, v127
	v_cmp_lt_f32_e64 s[46:47], |v127|, s62
	s_nop 1
	v_cndmask_b32_e64 v127, v127, v157, s[46:47]
	v_cndmask_b32_e32 v157, 0, v225, vcc
	v_sub_f32_e32 v127, v127, v157
	v_mul_f32_e32 v157, 0xbfb8aa3b, v130
	v_exp_f32_e32 v157, v157
	s_nop 0
	v_add_f32_e32 v157, 1.0, v157
	v_rcp_f32_e32 v157, v157
	s_nop 0
	v_fma_f32 v120, v157, v214, v120
	v_max_f32_e32 v120, 0xda24260, v120
	v_cmp_gt_f32_e32 vcc, s93, v120
	s_nop 1
	v_cndmask_b32_e64 v157, 0, 32, vcc
	v_ldexp_f32 v120, v120, v157
	v_log_f32_e32 v120, v120
	s_nop 0
	v_mul_f32_e32 v157, 0x3f317217, v120
	v_fma_f32 v157, v120, s95, -v157
	v_fmac_f32_e32 v157, 0x3377d1cf, v120
	v_fmac_f32_e32 v157, 0x3f317217, v120
	v_cmp_lt_f32_e64 s[46:47], |v120|, s62
	s_nop 1
	v_cndmask_b32_e64 v120, v120, v157, s[46:47]
	v_cndmask_b32_e32 v157, 0, v225, vcc
	v_sub_f32_e32 v210, v120, v157
	v_fma_f32 v120, v159, v215, v121
	v_max_f32_e32 v120, 0xda24260, v120
	v_cmp_gt_f32_e32 vcc, s93, v120
	s_nop 1
	v_cndmask_b32_e64 v121, 0, 32, vcc
	v_ldexp_f32 v120, v120, v121
	v_log_f32_e32 v120, v120
	s_nop 0
	v_mul_f32_e32 v121, 0x3f317217, v120
	v_fma_f32 v121, v120, s95, -v121
	v_fmac_f32_e32 v121, 0x3377d1cf, v120
	v_fmac_f32_e32 v121, 0x3f317217, v120
	v_cmp_lt_f32_e64 s[46:47], |v120|, s62
	s_nop 1
	v_cndmask_b32_e64 v120, v120, v121, s[46:47]
	v_cndmask_b32_e32 v121, 0, v225, vcc
	v_sub_f32_e32 v211, v120, v121
	v_mul_f32_e32 v120, 0xbfb8aa3b, v180
	v_exp_f32_e32 v120, v120
	v_mul_f32_e32 v121, 0xbfb8aa3b, v181
	v_exp_f32_e32 v121, v121
	v_add_f32_e32 v120, 1.0, v120
	v_rcp_f32_e32 v157, v120
	v_add_f32_e32 v121, 1.0, v121
	v_rcp_f32_e32 v159, v121
	v_mul_f32_e32 v120, 0x3fb8aa3b, v180
	v_fma_f32 v122, v157, v218, v122
	v_max_f32_e32 v122, 0xda24260, v122
	v_cmp_gt_f32_e32 vcc, s93, v122
	v_fmac_f32_e32 v123, v159, v219
	v_mul_f32_e32 v121, 0x3fb8aa3b, v181
	v_cndmask_b32_e64 v157, 0, 32, vcc
	v_ldexp_f32 v122, v122, v157
	v_log_f32_e32 v122, v122
	v_exp_f32_e32 v120, v120
	v_exp_f32_e32 v121, v121
	v_mul_f32_e32 v157, 0x3f317217, v122
	v_fma_f32 v157, v122, s95, -v157
	v_fmac_f32_e32 v157, 0x3377d1cf, v122
	v_fmac_f32_e32 v157, 0x3f317217, v122
	v_cmp_lt_f32_e64 s[46:47], |v122|, s62
	v_add_f32_e32 v120, 1.0, v120
	v_add_f32_e32 v121, 1.0, v121
	v_cndmask_b32_e64 v122, v122, v157, s[46:47]
	v_cndmask_b32_e32 v157, 0, v225, vcc
	v_sub_f32_e32 v212, v122, v157
	v_max_f32_e32 v122, 0xda24260, v123
	v_cmp_gt_f32_e32 vcc, s93, v122
	v_rcp_f32_e32 v120, v120
	v_rcp_f32_e32 v121, v121
	v_cndmask_b32_e64 v123, 0, 32, vcc
	v_ldexp_f32 v122, v122, v123
	v_log_f32_e32 v122, v122
	v_pk_mul_f32 v[120:121], v[120:121], v[218:219]
	v_mul_f32_e32 v123, 0x3f317217, v122
	v_fma_f32 v123, v122, s95, -v123
	v_fmac_f32_e32 v123, 0x3377d1cf, v122
	v_fmac_f32_e32 v123, 0x3f317217, v122
	v_cmp_lt_f32_e64 s[46:47], |v122|, s62
	s_nop 1
	v_cndmask_b32_e64 v122, v122, v123, s[46:47]
	v_cndmask_b32_e32 v123, 0, v225, vcc
	v_sub_f32_e32 v213, v122, v123
	v_pk_mul_f32 v[122:123], v[208:209], v[214:215]
	global_store_dwordx4 v[178:179], v[124:127], off
	global_store_dwordx4 v[178:179], v[210:213], off offset:16

.LBB0_312:
	s_andn2_b64 vcc, exec, s[36:37]
	s_cbranch_vccnz .LBB0_314
	v_mul_f32_e32 v120, 0xbfb8aa3b, v134
	v_exp_f32_e32 v120, v120
	v_mul_f32_e32 v159, 0x3fb8aa3b, v179
	v_exp_f32_e32 v159, v159
	v_add_f32_e32 v120, 1.0, v120
	v_rcp_f32_e32 v131, v120
	v_mul_f32_e32 v120, 0x3fb8aa3b, v134
	v_exp_f32_e32 v120, v120
	v_add_f32_e32 v159, 1.0, v159
	v_rcp_f32_e32 v205, v159
	v_mul_f32_e32 v159, 0x3fb8aa3b, v133
	v_add_f32_e32 v120, 1.0, v120
	v_rcp_f32_e32 v182, v120
	v_mul_f32_e32 v120, 0xbfb8aa3b, v135
	v_exp_f32_e32 v120, v120
	v_exp_f32_e32 v159, v159
	v_add_f32_e32 v120, 1.0, v120
	v_rcp_f32_e32 v157, v120
	v_mul_f32_e32 v120, 0x3fb8aa3b, v135
	v_exp_f32_e32 v120, v120
	v_add_f32_e32 v159, 1.0, v159
	v_rcp_f32_e32 v209, v159
	v_add_f32_e32 v120, 1.0, v120
	v_rcp_f32_e32 v183, v120
	v_bfe_u32 v124, v184, 6, 2
	v_bfe_u32 v125, v184, 4, 2
	v_lshlrev_b32_e32 v124, 7, v124
	v_lshl_add_u32 v124, v125, 5, v124
	v_add_u32_e32 v124, 0x21800, v124
	ds_read_b128 v[120:123], v124 offset:16
	ds_read_b128 v[124:127], v124
	s_waitcnt lgkmcnt(1)
	v_pk_add_f32 v[214:215], v[120:121], 1.0 op_sel_hi:[1,0] neg_lo:[1,0] neg_hi:[1,0]
	s_waitcnt lgkmcnt(0)
	v_pk_add_f32 v[202:203], v[124:125], 1.0 op_sel_hi:[1,0] neg_lo:[1,0] neg_hi:[1,0]
	v_pk_add_f32 v[206:207], v[126:127], 1.0 op_sel_hi:[1,0] neg_lo:[1,0] neg_hi:[1,0]
	v_fma_f32 v124, v131, v202, v124
	v_max_f32_e32 v124, 0xda24260, v124
	v_cmp_gt_f32_e32 vcc, s93, v124
	v_fma_f32 v125, v157, v203, v125
	v_max_f32_e32 v125, 0xda24260, v125
	v_cndmask_b32_e64 v131, 0, 32, vcc
	v_ldexp_f32 v124, v124, v131
	v_log_f32_e32 v124, v124
	v_mul_f32_e32 v157, 0x3fb8aa3b, v178
	v_exp_f32_e32 v157, v157
	v_pk_add_f32 v[218:219], v[122:123], 1.0 op_sel_hi:[1,0] neg_lo:[1,0] neg_hi:[1,0]
	v_mul_f32_e32 v131, 0x3f317217, v124
	v_fma_f32 v131, v124, s95, -v131
	v_fmac_f32_e32 v131, 0x3377d1cf, v124
	v_fmac_f32_e32 v131, 0x3f317217, v124
	v_cmp_lt_f32_e64 s[46:47], |v124|, s62
	v_add_f32_e32 v157, 1.0, v157
	v_rcp_f32_e32 v204, v157
	v_cndmask_b32_e64 v124, v124, v131, s[46:47]
	v_cndmask_b32_e32 v131, 0, v225, vcc
	v_cmp_gt_f32_e32 vcc, s93, v125
	v_sub_f32_e32 v124, v124, v131
	v_mul_f32_e32 v157, 0xbfb8aa3b, v179
	v_cndmask_b32_e64 v131, 0, 32, vcc
	v_ldexp_f32 v125, v125, v131
	v_log_f32_e32 v125, v125
	v_exp_f32_e32 v157, v157
	v_pk_mul_f32 v[202:203], v[182:183], v[202:203]
	v_pk_mul_f32 v[182:183], v[204:205], v[206:207]
	v_mul_f32_e32 v131, 0x3f317217, v125
	v_fma_f32 v131, v125, s95, -v131
	v_fmac_f32_e32 v131, 0x3377d1cf, v125
	v_fmac_f32_e32 v131, 0x3f317217, v125
	v_cmp_lt_f32_e64 s[46:47], |v125|, s62
	v_add_f32_e32 v157, 1.0, v157
	v_rcp_f32_e32 v157, v157
	v_cndmask_b32_e64 v125, v125, v131, s[46:47]
	v_cndmask_b32_e32 v131, 0, v225, vcc
	v_sub_f32_e32 v125, v125, v131
	v_mul_f32_e32 v131, 0xbfb8aa3b, v178
	v_exp_f32_e32 v131, v131
	v_fmac_f32_e32 v127, v157, v207
	v_max_f32_e32 v127, 0xda24260, v127
	v_mul_f32_e32 v157, 0x3fb8aa3b, v132
	v_add_f32_e32 v131, 1.0, v131
	v_rcp_f32_e32 v131, v131
	v_exp_f32_e32 v157, v157
	v_lshl_add_u64 v[204:205], v[146:147], 0, v[128:129]
	v_fma_f32 v126, v131, v206, v126
	v_max_f32_e32 v126, 0xda24260, v126
	v_cmp_gt_f32_e32 vcc, s93, v126
	v_add_f32_e32 v157, 1.0, v157
	v_rcp_f32_e32 v208, v157
	v_cndmask_b32_e64 v131, 0, 32, vcc
	v_ldexp_f32 v126, v126, v131
	v_log_f32_e32 v126, v126
	v_mul_f32_e32 v157, 0xbfb8aa3b, v133
	v_exp_f32_e32 v157, v157
	v_mul_f32_e32 v131, 0x3f317217, v126
	v_fma_f32 v131, v126, s95, -v131
	v_fmac_f32_e32 v131, 0x3377d1cf, v126
	v_fmac_f32_e32 v131, 0x3f317217, v126
	v_cmp_lt_f32_e64 s[46:47], |v126|, s62
	v_add_f32_e32 v157, 1.0, v157
	v_rcp_f32_e32 v157, v157
	v_cndmask_b32_e64 v126, v126, v131, s[46:47]
	v_cndmask_b32_e32 v131, 0, v225, vcc
	v_cmp_gt_f32_e32 vcc, s93, v127
	v_sub_f32_e32 v126, v126, v131
	s_nop 0
	v_cndmask_b32_e64 v131, 0, 32, vcc
	v_ldexp_f32 v127, v127, v131
	v_log_f32_e32 v127, v127
	s_nop 0
	v_mul_f32_e32 v131, 0x3f317217, v127
	v_fma_f32 v131, v127, s95, -v131
	v_fmac_f32_e32 v131, 0x3377d1cf, v127
	v_fmac_f32_e32 v131, 0x3f317217, v127
	v_cmp_lt_f32_e64 s[46:47], |v127|, s62
	s_nop 1
	v_cndmask_b32_e64 v127, v127, v131, s[46:47]
	v_cndmask_b32_e32 v131, 0, v225, vcc
	v_sub_f32_e32 v127, v127, v131
	v_mul_f32_e32 v131, 0xbfb8aa3b, v132
	v_exp_f32_e32 v131, v131
	s_nop 0
	v_add_f32_e32 v131, 1.0, v131
	v_rcp_f32_e32 v131, v131
	s_nop 0
	v_fma_f32 v120, v131, v214, v120
	v_max_f32_e32 v120, 0xda24260, v120
	v_cmp_gt_f32_e32 vcc, s93, v120
	s_nop 1
	v_cndmask_b32_e64 v131, 0, 32, vcc
	v_ldexp_f32 v120, v120, v131
	v_log_f32_e32 v120, v120
	s_nop 0
	v_mul_f32_e32 v131, 0x3f317217, v120
	v_fma_f32 v131, v120, s95, -v131
	v_fmac_f32_e32 v131, 0x3377d1cf, v120
	v_fmac_f32_e32 v131, 0x3f317217, v120
	v_cmp_lt_f32_e64 s[46:47], |v120|, s62
	s_nop 1
	v_cndmask_b32_e64 v120, v120, v131, s[46:47]
	v_cndmask_b32_e32 v131, 0, v225, vcc
	v_sub_f32_e32 v210, v120, v131
	v_fma_f32 v120, v157, v215, v121
	v_max_f32_e32 v120, 0xda24260, v120
	v_cmp_gt_f32_e32 vcc, s93, v120
	s_nop 1
	v_cndmask_b32_e64 v121, 0, 32, vcc
	v_ldexp_f32 v120, v120, v121
	v_log_f32_e32 v120, v120
	s_nop 0
	v_mul_f32_e32 v121, 0x3f317217, v120
	v_fma_f32 v121, v120, s95, -v121
	v_fmac_f32_e32 v121, 0x3377d1cf, v120
	v_fmac_f32_e32 v121, 0x3f317217, v120
	v_cmp_lt_f32_e64 s[46:47], |v120|, s62
	s_nop 1
	v_cndmask_b32_e64 v120, v120, v121, s[46:47]
	v_cndmask_b32_e32 v121, 0, v225, vcc
	v_sub_f32_e32 v211, v120, v121
	v_mul_f32_e32 v120, 0xbfb8aa3b, v180
	v_exp_f32_e32 v120, v120
	v_mul_f32_e32 v121, 0xbfb8aa3b, v181
	v_exp_f32_e32 v121, v121
	v_add_f32_e32 v120, 1.0, v120
	v_rcp_f32_e32 v131, v120
	v_add_f32_e32 v121, 1.0, v121
	v_rcp_f32_e32 v157, v121
	v_mul_f32_e32 v120, 0x3fb8aa3b, v180
	v_fma_f32 v122, v131, v218, v122
	v_max_f32_e32 v122, 0xda24260, v122
	v_cmp_gt_f32_e32 vcc, s93, v122
	v_fmac_f32_e32 v123, v157, v219
	v_mul_f32_e32 v121, 0x3fb8aa3b, v181
	v_cndmask_b32_e64 v131, 0, 32, vcc
	v_ldexp_f32 v122, v122, v131
	v_log_f32_e32 v122, v122
	v_exp_f32_e32 v120, v120
	v_exp_f32_e32 v121, v121
	v_mul_f32_e32 v131, 0x3f317217, v122
	v_fma_f32 v131, v122, s95, -v131
	v_fmac_f32_e32 v131, 0x3377d1cf, v122
	v_fmac_f32_e32 v131, 0x3f317217, v122
	v_cmp_lt_f32_e64 s[46:47], |v122|, s62
	v_add_f32_e32 v120, 1.0, v120
	v_add_f32_e32 v121, 1.0, v121
	v_cndmask_b32_e64 v122, v122, v131, s[46:47]
	v_cndmask_b32_e32 v131, 0, v225, vcc
	v_sub_f32_e32 v212, v122, v131
	v_max_f32_e32 v122, 0xda24260, v123
	v_cmp_gt_f32_e32 vcc, s93, v122
	v_rcp_f32_e32 v120, v120
	v_rcp_f32_e32 v121, v121
	v_cndmask_b32_e64 v123, 0, 32, vcc
	v_ldexp_f32 v122, v122, v123
	v_log_f32_e32 v122, v122
	v_pk_mul_f32 v[120:121], v[120:121], v[218:219]
	v_mul_f32_e32 v123, 0x3f317217, v122
	v_fma_f32 v123, v122, s95, -v123
	v_fmac_f32_e32 v123, 0x3377d1cf, v122
	v_fmac_f32_e32 v123, 0x3f317217, v122
	v_cmp_lt_f32_e64 s[46:47], |v122|, s62
	s_nop 1
	v_cndmask_b32_e64 v122, v122, v123, s[46:47]
	v_cndmask_b32_e32 v123, 0, v225, vcc
	v_sub_f32_e32 v213, v122, v123
	v_pk_mul_f32 v[122:123], v[208:209], v[214:215]
	global_store_dwordx4 v[204:205], v[124:127], off
	global_store_dwordx4 v[204:205], v[210:213], off offset:16

.LBB0_324:
	s_andn2_b64 vcc, exec, s[36:37]
	s_cbranch_vccnz .LBB0_326
	v_bfe_u32 v116, v184, 6, 2
	v_bfe_u32 v117, v184, 4, 2
	v_lshlrev_b32_e32 v116, 7, v116
	v_lshl_add_u32 v116, v117, 5, v116
	v_add_u32_e32 v116, 0x21800, v116
	ds_read_b128 v[112:115], v116 offset:528
	ds_read_b128 v[116:119], v116 offset:512
	v_mul_f32_e32 v132, 0xbfb8aa3b, v124
	v_exp_f32_e32 v132, v132
	v_mul_f32_e32 v133, 0xbfb8aa3b, v125
	v_exp_f32_e32 v133, v133
	v_mul_f32_e32 v161, 0x3fb8aa3b, v127
	v_add_f32_e32 v132, 1.0, v132
	v_rcp_f32_e32 v157, v132
	v_add_f32_e32 v133, 1.0, v133
	v_rcp_f32_e32 v159, v133
	v_exp_f32_e32 v161, v161
	v_mul_f32_e32 v132, 0x3fb8aa3b, v124
	v_mul_f32_e32 v133, 0x3fb8aa3b, v125
	v_exp_f32_e32 v132, v132
	v_add_f32_e32 v161, 1.0, v161
	v_rcp_f32_e32 v179, v161
	v_mul_f32_e32 v161, 0x3fb8aa3b, v123
	v_exp_f32_e32 v133, v133
	v_exp_f32_e32 v161, v161
	v_add_f32_e32 v132, 1.0, v132
	v_rcp_f32_e32 v132, v132
	v_add_f32_e32 v133, 1.0, v133
	v_add_f32_e32 v161, 1.0, v161
	v_rcp_f32_e32 v133, v133
	v_rcp_f32_e32 v183, v161
	v_lshl_add_u64 v[128:129], v[150:151], 0, v[128:129]
	s_waitcnt lgkmcnt(1)
	v_pk_add_f32 v[206:207], v[112:113], 1.0 op_sel_hi:[1,0] neg_lo:[1,0] neg_hi:[1,0]
	s_waitcnt lgkmcnt(0)
	v_pk_add_f32 v[134:135], v[116:117], 1.0 op_sel_hi:[1,0] neg_lo:[1,0] neg_hi:[1,0]
	v_pk_add_f32 v[180:181], v[118:119], 1.0 op_sel_hi:[1,0] neg_lo:[1,0] neg_hi:[1,0]
	v_fma_f32 v116, v157, v134, v116
	v_max_f32_e32 v116, 0xda24260, v116
	v_cmp_gt_f32_e32 vcc, s93, v116
	v_fma_f32 v117, v159, v135, v117
	v_max_f32_e32 v117, 0xda24260, v117
	v_cndmask_b32_e64 v157, 0, 32, vcc
	v_ldexp_f32 v116, v116, v157
	v_log_f32_e32 v116, v116
	v_mul_f32_e32 v159, 0x3fb8aa3b, v126
	v_exp_f32_e32 v159, v159
	v_pk_add_f32 v[208:209], v[114:115], 1.0 op_sel_hi:[1,0] neg_lo:[1,0] neg_hi:[1,0]
	v_mul_f32_e32 v157, 0x3f317217, v116
	v_fma_f32 v157, v116, s95, -v157
	v_fmac_f32_e32 v157, 0x3377d1cf, v116
	v_fmac_f32_e32 v157, 0x3f317217, v116
	v_cmp_lt_f32_e64 s[46:47], |v116|, s62
	v_add_f32_e32 v159, 1.0, v159
	v_rcp_f32_e32 v178, v159
	v_cndmask_b32_e64 v116, v116, v157, s[46:47]
	v_cndmask_b32_e32 v157, 0, v225, vcc
	v_cmp_gt_f32_e32 vcc, s93, v117
	v_sub_f32_e32 v116, v116, v157
	v_mul_f32_e32 v159, 0xbfb8aa3b, v127
	v_cndmask_b32_e64 v157, 0, 32, vcc
	v_ldexp_f32 v117, v117, v157
	v_log_f32_e32 v117, v117
	v_exp_f32_e32 v159, v159
	v_pk_mul_f32 v[134:135], v[132:133], v[134:135]
	v_pk_mul_f32 v[132:133], v[178:179], v[180:181]
	v_mul_f32_e32 v157, 0x3f317217, v117
	v_fma_f32 v157, v117, s95, -v157
	v_fmac_f32_e32 v157, 0x3377d1cf, v117
	v_fmac_f32_e32 v157, 0x3f317217, v117
	v_cmp_lt_f32_e64 s[46:47], |v117|, s62
	v_add_f32_e32 v159, 1.0, v159
	v_rcp_f32_e32 v159, v159
	v_cndmask_b32_e64 v117, v117, v157, s[46:47]
	v_cndmask_b32_e32 v157, 0, v225, vcc
	v_sub_f32_e32 v117, v117, v157
	v_mul_f32_e32 v157, 0xbfb8aa3b, v126
	v_exp_f32_e32 v157, v157
	v_fmac_f32_e32 v119, v159, v181
	v_max_f32_e32 v119, 0xda24260, v119
	v_mul_f32_e32 v159, 0x3fb8aa3b, v122
	v_add_f32_e32 v157, 1.0, v157
	v_rcp_f32_e32 v157, v157
	v_exp_f32_e32 v159, v159
	v_fma_f32 v118, v157, v180, v118
	v_max_f32_e32 v118, 0xda24260, v118
	v_cmp_gt_f32_e32 vcc, s93, v118
	v_add_f32_e32 v159, 1.0, v159
	v_rcp_f32_e32 v182, v159
	v_cndmask_b32_e64 v157, 0, 32, vcc
	v_ldexp_f32 v118, v118, v157
	v_log_f32_e32 v118, v118
	v_mul_f32_e32 v159, 0xbfb8aa3b, v123
	v_exp_f32_e32 v159, v159
	v_mul_f32_e32 v157, 0x3f317217, v118
	v_fma_f32 v157, v118, s95, -v157
	v_fmac_f32_e32 v157, 0x3377d1cf, v118
	v_fmac_f32_e32 v157, 0x3f317217, v118
	v_cmp_lt_f32_e64 s[46:47], |v118|, s62
	v_add_f32_e32 v159, 1.0, v159
	v_rcp_f32_e32 v159, v159
	v_cndmask_b32_e64 v118, v118, v157, s[46:47]
	v_cndmask_b32_e32 v157, 0, v225, vcc
	v_cmp_gt_f32_e32 vcc, s93, v119
	v_sub_f32_e32 v118, v118, v157
	s_nop 0
	v_cndmask_b32_e64 v157, 0, 32, vcc
	v_ldexp_f32 v119, v119, v157
	v_log_f32_e32 v119, v119
	s_nop 0
	v_mul_f32_e32 v157, 0x3f317217, v119
	v_fma_f32 v157, v119, s95, -v157
	v_fmac_f32_e32 v157, 0x3377d1cf, v119
	v_fmac_f32_e32 v157, 0x3f317217, v119
	v_cmp_lt_f32_e64 s[46:47], |v119|, s62
	s_nop 1
	v_cndmask_b32_e64 v119, v119, v157, s[46:47]
	v_cndmask_b32_e32 v157, 0, v225, vcc
	v_sub_f32_e32 v119, v119, v157
	v_mul_f32_e32 v157, 0xbfb8aa3b, v122
	v_exp_f32_e32 v157, v157
	s_nop 0
	v_add_f32_e32 v157, 1.0, v157
	v_rcp_f32_e32 v157, v157
	s_nop 0
	v_fma_f32 v112, v157, v206, v112
	v_max_f32_e32 v112, 0xda24260, v112
	v_cmp_gt_f32_e32 vcc, s93, v112
	s_nop 1
	v_cndmask_b32_e64 v157, 0, 32, vcc
	v_ldexp_f32 v112, v112, v157
	v_log_f32_e32 v112, v112
	s_nop 0
	v_mul_f32_e32 v157, 0x3f317217, v112
	v_fma_f32 v157, v112, s95, -v157
	v_fmac_f32_e32 v157, 0x3377d1cf, v112
	v_fmac_f32_e32 v157, 0x3f317217, v112
	v_cmp_lt_f32_e64 s[46:47], |v112|, s62
	s_nop 1
	v_cndmask_b32_e64 v112, v112, v157, s[46:47]
	v_cndmask_b32_e32 v157, 0, v225, vcc
	v_sub_f32_e32 v202, v112, v157
	v_fma_f32 v112, v159, v207, v113
	v_max_f32_e32 v112, 0xda24260, v112
	v_cmp_gt_f32_e32 vcc, s93, v112
	s_nop 1
	v_cndmask_b32_e64 v113, 0, 32, vcc
	v_ldexp_f32 v112, v112, v113
	v_log_f32_e32 v112, v112
	s_nop 0
	v_mul_f32_e32 v113, 0x3f317217, v112
	v_fma_f32 v113, v112, s95, -v113
	v_fmac_f32_e32 v113, 0x3377d1cf, v112
	v_fmac_f32_e32 v113, 0x3f317217, v112
	v_cmp_lt_f32_e64 s[46:47], |v112|, s62
	s_nop 1
	v_cndmask_b32_e64 v112, v112, v113, s[46:47]
	v_cndmask_b32_e32 v113, 0, v225, vcc
	v_sub_f32_e32 v203, v112, v113
	v_mul_f32_e32 v112, 0xbfb8aa3b, v130
	v_exp_f32_e32 v112, v112
	v_mul_f32_e32 v113, 0xbfb8aa3b, v131
	v_exp_f32_e32 v113, v113
	v_add_f32_e32 v112, 1.0, v112
	v_rcp_f32_e32 v157, v112
	v_add_f32_e32 v113, 1.0, v113
	v_rcp_f32_e32 v159, v113
	v_mul_f32_e32 v112, 0x3fb8aa3b, v130
	v_fma_f32 v114, v157, v208, v114
	v_max_f32_e32 v114, 0xda24260, v114
	v_cmp_gt_f32_e32 vcc, s93, v114
	v_fmac_f32_e32 v115, v159, v209
	v_mul_f32_e32 v113, 0x3fb8aa3b, v131
	v_cndmask_b32_e64 v157, 0, 32, vcc
	v_ldexp_f32 v114, v114, v157
	v_log_f32_e32 v114, v114
	v_exp_f32_e32 v112, v112
	v_exp_f32_e32 v113, v113
	v_mul_f32_e32 v157, 0x3f317217, v114
	v_fma_f32 v157, v114, s95, -v157
	v_fmac_f32_e32 v157, 0x3377d1cf, v114
	v_fmac_f32_e32 v157, 0x3f317217, v114
	v_cmp_lt_f32_e64 s[46:47], |v114|, s62
	v_add_f32_e32 v112, 1.0, v112
	v_add_f32_e32 v113, 1.0, v113
	v_cndmask_b32_e64 v114, v114, v157, s[46:47]
	v_cndmask_b32_e32 v157, 0, v225, vcc
	v_sub_f32_e32 v204, v114, v157
	v_max_f32_e32 v114, 0xda24260, v115
	v_cmp_gt_f32_e32 vcc, s93, v114
	v_rcp_f32_e32 v112, v112
	v_rcp_f32_e32 v113, v113
	v_cndmask_b32_e64 v115, 0, 32, vcc
	v_ldexp_f32 v114, v114, v115
	v_log_f32_e32 v114, v114
	v_pk_mul_f32 v[112:113], v[112:113], v[208:209]
	v_mul_f32_e32 v115, 0x3f317217, v114
	v_fma_f32 v115, v114, s95, -v115
	v_fmac_f32_e32 v115, 0x3377d1cf, v114
	v_fmac_f32_e32 v115, 0x3f317217, v114
	v_cmp_lt_f32_e64 s[46:47], |v114|, s62
	s_nop 1
	v_cndmask_b32_e64 v114, v114, v115, s[46:47]
	v_cndmask_b32_e32 v115, 0, v225, vcc
	v_sub_f32_e32 v205, v114, v115
	v_pk_mul_f32 v[114:115], v[182:183], v[206:207]
	global_store_dwordx4 v[128:129], v[116:119], off
	global_store_dwordx4 v[128:129], v[202:205], off offset:16

.LBB0_336:
	s_andn2_b64 vcc, exec, s[36:37]
	s_cbranch_vccnz .LBB0_338
	v_mul_f32_e32 v112, 0xbfb8aa3b, v126
	v_exp_f32_e32 v112, v112
	v_mul_f32_e32 v159, 0x3fb8aa3b, v129
	v_exp_f32_e32 v159, v159
	v_add_f32_e32 v112, 1.0, v112
	v_rcp_f32_e32 v123, v112
	v_mul_f32_e32 v112, 0x3fb8aa3b, v126
	v_exp_f32_e32 v112, v112
	v_add_f32_e32 v159, 1.0, v159
	v_rcp_f32_e32 v179, v159
	v_mul_f32_e32 v159, 0x3fb8aa3b, v125
	v_add_f32_e32 v112, 1.0, v112
	v_rcp_f32_e32 v132, v112
	v_mul_f32_e32 v112, 0xbfb8aa3b, v127
	v_exp_f32_e32 v112, v112
	v_exp_f32_e32 v159, v159
	v_add_f32_e32 v112, 1.0, v112
	v_rcp_f32_e32 v157, v112
	v_mul_f32_e32 v112, 0x3fb8aa3b, v127
	v_exp_f32_e32 v112, v112
	v_add_f32_e32 v159, 1.0, v159
	v_rcp_f32_e32 v183, v159
	v_add_f32_e32 v112, 1.0, v112
	v_rcp_f32_e32 v133, v112
	v_bfe_u32 v116, v184, 6, 2
	v_bfe_u32 v117, v184, 4, 2
	v_lshlrev_b32_e32 v116, 7, v116
	v_lshl_add_u32 v116, v117, 5, v116
	v_add_u32_e32 v116, 0x21800, v116
	ds_read_b128 v[112:115], v116 offset:16
	ds_read_b128 v[116:119], v116
	s_waitcnt lgkmcnt(1)
	v_pk_add_f32 v[206:207], v[112:113], 1.0 op_sel_hi:[1,0] neg_lo:[1,0] neg_hi:[1,0]
	s_waitcnt lgkmcnt(0)
	v_pk_add_f32 v[134:135], v[116:117], 1.0 op_sel_hi:[1,0] neg_lo:[1,0] neg_hi:[1,0]
	v_pk_add_f32 v[180:181], v[118:119], 1.0 op_sel_hi:[1,0] neg_lo:[1,0] neg_hi:[1,0]
	v_fma_f32 v116, v123, v134, v116
	v_max_f32_e32 v116, 0xda24260, v116
	v_cmp_gt_f32_e32 vcc, s93, v116
	v_fma_f32 v117, v157, v135, v117
	v_max_f32_e32 v117, 0xda24260, v117
	v_cndmask_b32_e64 v123, 0, 32, vcc
	v_ldexp_f32 v116, v116, v123
	v_log_f32_e32 v116, v116
	v_mul_f32_e32 v157, 0x3fb8aa3b, v128
	v_exp_f32_e32 v157, v157
	v_pk_add_f32 v[208:209], v[114:115], 1.0 op_sel_hi:[1,0] neg_lo:[1,0] neg_hi:[1,0]
	v_mul_f32_e32 v123, 0x3f317217, v116
	v_fma_f32 v123, v116, s95, -v123
	v_fmac_f32_e32 v123, 0x3377d1cf, v116
	v_fmac_f32_e32 v123, 0x3f317217, v116
	v_cmp_lt_f32_e64 s[46:47], |v116|, s62
	v_add_f32_e32 v157, 1.0, v157
	v_rcp_f32_e32 v178, v157
	v_cndmask_b32_e64 v116, v116, v123, s[46:47]
	v_cndmask_b32_e32 v123, 0, v225, vcc
	v_cmp_gt_f32_e32 vcc, s93, v117
	v_sub_f32_e32 v116, v116, v123
	v_mul_f32_e32 v157, 0xbfb8aa3b, v129
	v_cndmask_b32_e64 v123, 0, 32, vcc
	v_ldexp_f32 v117, v117, v123
	v_log_f32_e32 v117, v117
	v_exp_f32_e32 v157, v157
	v_pk_mul_f32 v[134:135], v[132:133], v[134:135]
	v_pk_mul_f32 v[132:133], v[178:179], v[180:181]
	v_mul_f32_e32 v123, 0x3f317217, v117
	v_fma_f32 v123, v117, s95, -v123
	v_fmac_f32_e32 v123, 0x3377d1cf, v117
	v_fmac_f32_e32 v123, 0x3f317217, v117
	v_cmp_lt_f32_e64 s[46:47], |v117|, s62
	v_add_f32_e32 v157, 1.0, v157
	v_rcp_f32_e32 v157, v157
	v_cndmask_b32_e64 v117, v117, v123, s[46:47]
	v_cndmask_b32_e32 v123, 0, v225, vcc
	v_sub_f32_e32 v117, v117, v123
	v_mul_f32_e32 v123, 0xbfb8aa3b, v128
	v_exp_f32_e32 v123, v123
	v_fmac_f32_e32 v119, v157, v181
	v_max_f32_e32 v119, 0xda24260, v119
	v_mul_f32_e32 v157, 0x3fb8aa3b, v124
	v_add_f32_e32 v123, 1.0, v123
	v_rcp_f32_e32 v123, v123
	v_exp_f32_e32 v157, v157
	v_lshl_add_u64 v[178:179], v[146:147], 0, v[120:121]
	v_fma_f32 v118, v123, v180, v118
	v_max_f32_e32 v118, 0xda24260, v118
	v_cmp_gt_f32_e32 vcc, s93, v118
	v_add_f32_e32 v157, 1.0, v157
	v_rcp_f32_e32 v182, v157
	v_cndmask_b32_e64 v123, 0, 32, vcc
	v_ldexp_f32 v118, v118, v123
	v_log_f32_e32 v118, v118
	v_mul_f32_e32 v157, 0xbfb8aa3b, v125
	v_exp_f32_e32 v157, v157
	v_mul_f32_e32 v123, 0x3f317217, v118
	v_fma_f32 v123, v118, s95, -v123
	v_fmac_f32_e32 v123, 0x3377d1cf, v118
	v_fmac_f32_e32 v123, 0x3f317217, v118
	v_cmp_lt_f32_e64 s[46:47], |v118|, s62
	v_add_f32_e32 v157, 1.0, v157
	v_rcp_f32_e32 v157, v157
	v_cndmask_b32_e64 v118, v118, v123, s[46:47]
	v_cndmask_b32_e32 v123, 0, v225, vcc
	v_cmp_gt_f32_e32 vcc, s93, v119
	v_sub_f32_e32 v118, v118, v123
	s_nop 0
	v_cndmask_b32_e64 v123, 0, 32, vcc
	v_ldexp_f32 v119, v119, v123
	v_log_f32_e32 v119, v119
	s_nop 0
	v_mul_f32_e32 v123, 0x3f317217, v119
	v_fma_f32 v123, v119, s95, -v123
	v_fmac_f32_e32 v123, 0x3377d1cf, v119
	v_fmac_f32_e32 v123, 0x3f317217, v119
	v_cmp_lt_f32_e64 s[46:47], |v119|, s62
	s_nop 1
	v_cndmask_b32_e64 v119, v119, v123, s[46:47]
	v_cndmask_b32_e32 v123, 0, v225, vcc
	v_sub_f32_e32 v119, v119, v123
	v_mul_f32_e32 v123, 0xbfb8aa3b, v124
	v_exp_f32_e32 v123, v123
	s_nop 0
	v_add_f32_e32 v123, 1.0, v123
	v_rcp_f32_e32 v123, v123
	s_nop 0
	v_fma_f32 v112, v123, v206, v112
	v_max_f32_e32 v112, 0xda24260, v112
	v_cmp_gt_f32_e32 vcc, s93, v112
	s_nop 1
	v_cndmask_b32_e64 v123, 0, 32, vcc
	v_ldexp_f32 v112, v112, v123
	v_log_f32_e32 v112, v112
	s_nop 0
	v_mul_f32_e32 v123, 0x3f317217, v112
	v_fma_f32 v123, v112, s95, -v123
	v_fmac_f32_e32 v123, 0x3377d1cf, v112
	v_fmac_f32_e32 v123, 0x3f317217, v112
	v_cmp_lt_f32_e64 s[46:47], |v112|, s62
	s_nop 1
	v_cndmask_b32_e64 v112, v112, v123, s[46:47]
	v_cndmask_b32_e32 v123, 0, v225, vcc
	v_sub_f32_e32 v202, v112, v123
	v_fma_f32 v112, v157, v207, v113
	v_max_f32_e32 v112, 0xda24260, v112
	v_cmp_gt_f32_e32 vcc, s93, v112
	s_nop 1
	v_cndmask_b32_e64 v113, 0, 32, vcc
	v_ldexp_f32 v112, v112, v113
	v_log_f32_e32 v112, v112
	s_nop 0
	v_mul_f32_e32 v113, 0x3f317217, v112
	v_fma_f32 v113, v112, s95, -v113
	v_fmac_f32_e32 v113, 0x3377d1cf, v112
	v_fmac_f32_e32 v113, 0x3f317217, v112
	v_cmp_lt_f32_e64 s[46:47], |v112|, s62
	s_nop 1
	v_cndmask_b32_e64 v112, v112, v113, s[46:47]
	v_cndmask_b32_e32 v113, 0, v225, vcc
	v_sub_f32_e32 v203, v112, v113
	v_mul_f32_e32 v112, 0xbfb8aa3b, v130
	v_exp_f32_e32 v112, v112
	v_mul_f32_e32 v113, 0xbfb8aa3b, v131
	v_exp_f32_e32 v113, v113
	v_add_f32_e32 v112, 1.0, v112
	v_rcp_f32_e32 v123, v112
	v_add_f32_e32 v113, 1.0, v113
	v_rcp_f32_e32 v157, v113
	v_mul_f32_e32 v112, 0x3fb8aa3b, v130
	v_fma_f32 v114, v123, v208, v114
	v_max_f32_e32 v114, 0xda24260, v114
	v_cmp_gt_f32_e32 vcc, s93, v114
	v_fmac_f32_e32 v115, v157, v209
	v_mul_f32_e32 v113, 0x3fb8aa3b, v131
	v_cndmask_b32_e64 v123, 0, 32, vcc
	v_ldexp_f32 v114, v114, v123
	v_log_f32_e32 v114, v114
	v_exp_f32_e32 v112, v112
	v_exp_f32_e32 v113, v113
	v_mul_f32_e32 v123, 0x3f317217, v114
	v_fma_f32 v123, v114, s95, -v123
	v_fmac_f32_e32 v123, 0x3377d1cf, v114
	v_fmac_f32_e32 v123, 0x3f317217, v114
	v_cmp_lt_f32_e64 s[46:47], |v114|, s62
	v_add_f32_e32 v112, 1.0, v112
	v_add_f32_e32 v113, 1.0, v113
	v_cndmask_b32_e64 v114, v114, v123, s[46:47]
	v_cndmask_b32_e32 v123, 0, v225, vcc
	v_sub_f32_e32 v204, v114, v123
	v_max_f32_e32 v114, 0xda24260, v115
	v_cmp_gt_f32_e32 vcc, s93, v114
	v_rcp_f32_e32 v112, v112
	v_rcp_f32_e32 v113, v113
	v_cndmask_b32_e64 v115, 0, 32, vcc
	v_ldexp_f32 v114, v114, v115
	v_log_f32_e32 v114, v114
	v_pk_mul_f32 v[112:113], v[112:113], v[208:209]
	v_mul_f32_e32 v115, 0x3f317217, v114
	v_fma_f32 v115, v114, s95, -v115
	v_fmac_f32_e32 v115, 0x3377d1cf, v114
	v_fmac_f32_e32 v115, 0x3f317217, v114
	v_cmp_lt_f32_e64 s[46:47], |v114|, s62
	s_nop 1
	v_cndmask_b32_e64 v114, v114, v115, s[46:47]
	v_cndmask_b32_e32 v115, 0, v225, vcc
	v_sub_f32_e32 v205, v114, v115
	v_pk_mul_f32 v[114:115], v[182:183], v[206:207]
	global_store_dwordx4 v[178:179], v[116:119], off
	global_store_dwordx4 v[178:179], v[202:205], off offset:16

.LBB0_348:
	s_andn2_b64 vcc, exec, s[36:37]
	s_cbranch_vccnz .LBB0_350
	v_bfe_u32 v108, v184, 6, 2
	v_bfe_u32 v109, v184, 4, 2
	v_lshlrev_b32_e32 v108, 7, v108
	v_lshl_add_u32 v108, v109, 5, v108
	v_add_u32_e32 v108, 0x21800, v108
	ds_read_b128 v[104:107], v108 offset:528
	ds_read_b128 v[108:111], v108 offset:512
	v_mul_f32_e32 v124, 0xbfb8aa3b, v116
	v_exp_f32_e32 v124, v124
	v_mul_f32_e32 v125, 0xbfb8aa3b, v117
	v_exp_f32_e32 v125, v125
	v_lshl_add_u64 v[120:121], v[150:151], 0, v[120:121]
	v_add_f32_e32 v124, 1.0, v124
	v_rcp_f32_e32 v128, v124
	v_add_f32_e32 v125, 1.0, v125
	v_rcp_f32_e32 v129, v125
	v_mul_f32_e32 v124, 0x3fb8aa3b, v116
	v_mul_f32_e32 v125, 0x3fb8aa3b, v117
	v_exp_f32_e32 v124, v124
	v_exp_f32_e32 v125, v125
	v_add_f32_e32 v124, 1.0, v124
	v_add_f32_e32 v125, 1.0, v125
	v_rcp_f32_e32 v124, v124
	v_rcp_f32_e32 v125, v125
	s_waitcnt lgkmcnt(1)
	v_pk_add_f32 v[134:135], v[104:105], 1.0 op_sel_hi:[1,0] neg_lo:[1,0] neg_hi:[1,0]
	s_waitcnt lgkmcnt(0)
	v_pk_add_f32 v[126:127], v[108:109], 1.0 op_sel_hi:[1,0] neg_lo:[1,0] neg_hi:[1,0]
	v_pk_add_f32 v[130:131], v[110:111], 1.0 op_sel_hi:[1,0] neg_lo:[1,0] neg_hi:[1,0]
	v_fma_f32 v108, v128, v126, v108
	v_max_f32_e32 v108, 0xda24260, v108
	v_cmp_gt_f32_e32 vcc, s93, v108
	v_fma_f32 v109, v129, v127, v109
	v_max_f32_e32 v109, 0xda24260, v109
	v_cndmask_b32_e64 v128, 0, 32, vcc
	v_ldexp_f32 v108, v108, v128
	v_log_f32_e32 v108, v108
	v_mul_f32_e32 v129, 0xbfb8aa3b, v119
	v_exp_f32_e32 v129, v129
	v_pk_add_f32 v[182:183], v[106:107], 1.0 op_sel_hi:[1,0] neg_lo:[1,0] neg_hi:[1,0]
	v_mul_f32_e32 v128, 0x3f317217, v108
	v_fma_f32 v128, v108, s95, -v128
	v_fmac_f32_e32 v128, 0x3377d1cf, v108
	v_fmac_f32_e32 v128, 0x3f317217, v108
	v_cmp_lt_f32_e64 s[46:47], |v108|, s62
	v_add_f32_e32 v129, 1.0, v129
	v_rcp_f32_e32 v133, v129
	v_cndmask_b32_e64 v108, v108, v128, s[46:47]
	v_cndmask_b32_e32 v128, 0, v225, vcc
	v_cmp_gt_f32_e32 vcc, s93, v109
	v_sub_f32_e32 v108, v108, v128
	v_fmac_f32_e32 v111, v133, v131
	v_cndmask_b32_e64 v128, 0, 32, vcc
	v_ldexp_f32 v109, v109, v128
	v_log_f32_e32 v109, v109
	v_max_f32_e32 v111, 0xda24260, v111
	v_mul_f32_e32 v133, 0xbfb8aa3b, v115
	v_exp_f32_e32 v133, v133
	v_mul_f32_e32 v128, 0x3f317217, v109
	v_fma_f32 v128, v109, s95, -v128
	v_fmac_f32_e32 v128, 0x3377d1cf, v109
	v_fmac_f32_e32 v128, 0x3f317217, v109
	v_cmp_lt_f32_e64 s[46:47], |v109|, s62
	v_add_f32_e32 v133, 1.0, v133
	v_rcp_f32_e32 v159, v133
	v_cndmask_b32_e64 v109, v109, v128, s[46:47]
	v_cndmask_b32_e32 v128, 0, v225, vcc
	v_sub_f32_e32 v109, v109, v128
	v_mul_f32_e32 v128, 0xbfb8aa3b, v118
	v_exp_f32_e32 v128, v128
	v_mul_f32_e32 v129, 0x3fb8aa3b, v119
	v_mul_f32_e32 v133, 0x3fb8aa3b, v115
	v_exp_f32_e32 v129, v129
	v_add_f32_e32 v128, 1.0, v128
	v_rcp_f32_e32 v132, v128
	v_mul_f32_e32 v128, 0x3fb8aa3b, v118
	v_exp_f32_e32 v128, v128
	v_exp_f32_e32 v133, v133
	v_fma_f32 v110, v132, v130, v110
	v_max_f32_e32 v110, 0xda24260, v110
	v_cmp_gt_f32_e32 vcc, s93, v110
	v_add_f32_e32 v128, 1.0, v128
	v_add_f32_e32 v129, 1.0, v129
	v_cndmask_b32_e64 v132, 0, 32, vcc
	v_ldexp_f32 v110, v110, v132
	v_log_f32_e32 v110, v110
	v_add_f32_e32 v133, 1.0, v133
	v_rcp_f32_e32 v128, v128
	v_rcp_f32_e32 v129, v129
	v_mul_f32_e32 v132, 0x3f317217, v110
	v_fma_f32 v132, v110, s95, -v132
	v_fmac_f32_e32 v132, 0x3377d1cf, v110
	v_fmac_f32_e32 v132, 0x3f317217, v110
	v_cmp_lt_f32_e64 s[46:47], |v110|, s62
	v_rcp_f32_e32 v133, v133
	v_pk_mul_f32 v[126:127], v[124:125], v[126:127]
	v_cndmask_b32_e64 v110, v110, v132, s[46:47]
	v_cndmask_b32_e32 v132, 0, v225, vcc
	v_cmp_gt_f32_e32 vcc, s93, v111
	v_sub_f32_e32 v110, v110, v132
	v_pk_mul_f32 v[124:125], v[128:129], v[130:131]
	v_cndmask_b32_e64 v132, 0, 32, vcc
	v_ldexp_f32 v111, v111, v132
	v_log_f32_e32 v111, v111
	s_nop 0
	v_mul_f32_e32 v132, 0x3f317217, v111
	v_fma_f32 v132, v111, s95, -v132
	v_fmac_f32_e32 v132, 0x3377d1cf, v111
	v_fmac_f32_e32 v132, 0x3f317217, v111
	v_cmp_lt_f32_e64 s[46:47], |v111|, s62
	s_nop 1
	v_cndmask_b32_e64 v111, v111, v132, s[46:47]
	v_cndmask_b32_e32 v132, 0, v225, vcc
	v_sub_f32_e32 v111, v111, v132
	v_mul_f32_e32 v132, 0xbfb8aa3b, v114
	v_exp_f32_e32 v132, v132
	s_nop 0
	v_add_f32_e32 v132, 1.0, v132
	v_rcp_f32_e32 v157, v132
	v_mul_f32_e32 v132, 0x3fb8aa3b, v114
	v_exp_f32_e32 v132, v132
	v_fma_f32 v104, v157, v134, v104
	v_max_f32_e32 v104, 0xda24260, v104
	v_cmp_gt_f32_e32 vcc, s93, v104
	v_add_f32_e32 v132, 1.0, v132
	v_rcp_f32_e32 v132, v132
	v_cndmask_b32_e64 v157, 0, 32, vcc
	v_ldexp_f32 v104, v104, v157
	v_log_f32_e32 v104, v104
	s_nop 0
	v_mul_f32_e32 v157, 0x3f317217, v104
	v_fma_f32 v157, v104, s95, -v157
	v_fmac_f32_e32 v157, 0x3377d1cf, v104
	v_fmac_f32_e32 v157, 0x3f317217, v104
	v_cmp_lt_f32_e64 s[46:47], |v104|, s62
	s_nop 1
	v_cndmask_b32_e64 v104, v104, v157, s[46:47]
	v_cndmask_b32_e32 v157, 0, v225, vcc
	v_sub_f32_e32 v178, v104, v157
	v_fma_f32 v104, v159, v135, v105
	v_max_f32_e32 v104, 0xda24260, v104
	v_cmp_gt_f32_e32 vcc, s93, v104
	s_nop 1
	v_cndmask_b32_e64 v105, 0, 32, vcc
	v_ldexp_f32 v104, v104, v105
	v_log_f32_e32 v104, v104
	s_nop 0
	v_mul_f32_e32 v105, 0x3f317217, v104
	v_fma_f32 v105, v104, s95, -v105
	v_fmac_f32_e32 v105, 0x3377d1cf, v104
	v_fmac_f32_e32 v105, 0x3f317217, v104
	v_cmp_lt_f32_e64 s[46:47], |v104|, s62
	s_nop 1
	v_cndmask_b32_e64 v104, v104, v105, s[46:47]
	v_cndmask_b32_e32 v105, 0, v225, vcc
	v_sub_f32_e32 v179, v104, v105
	v_mul_f32_e32 v104, 0xbfb8aa3b, v122
	v_exp_f32_e32 v104, v104
	v_mul_f32_e32 v105, 0xbfb8aa3b, v123
	v_exp_f32_e32 v105, v105
	v_add_f32_e32 v104, 1.0, v104
	v_rcp_f32_e32 v157, v104
	v_add_f32_e32 v105, 1.0, v105
	v_rcp_f32_e32 v159, v105
	v_mul_f32_e32 v104, 0x3fb8aa3b, v122
	v_fma_f32 v106, v157, v182, v106
	v_max_f32_e32 v106, 0xda24260, v106
	v_cmp_gt_f32_e32 vcc, s93, v106
	v_fmac_f32_e32 v107, v159, v183
	v_mul_f32_e32 v105, 0x3fb8aa3b, v123
	v_cndmask_b32_e64 v157, 0, 32, vcc
	v_ldexp_f32 v106, v106, v157
	v_log_f32_e32 v106, v106
	v_exp_f32_e32 v104, v104
	v_exp_f32_e32 v105, v105
	v_mul_f32_e32 v157, 0x3f317217, v106
	v_fma_f32 v157, v106, s95, -v157
	v_fmac_f32_e32 v157, 0x3377d1cf, v106
	v_fmac_f32_e32 v157, 0x3f317217, v106
	v_cmp_lt_f32_e64 s[46:47], |v106|, s62
	v_add_f32_e32 v104, 1.0, v104
	v_add_f32_e32 v105, 1.0, v105
	v_cndmask_b32_e64 v106, v106, v157, s[46:47]
	v_cndmask_b32_e32 v157, 0, v225, vcc
	v_sub_f32_e32 v180, v106, v157
	v_max_f32_e32 v106, 0xda24260, v107
	v_cmp_gt_f32_e32 vcc, s93, v106
	v_rcp_f32_e32 v104, v104
	v_rcp_f32_e32 v105, v105
	v_cndmask_b32_e64 v107, 0, 32, vcc
	v_ldexp_f32 v106, v106, v107
	v_log_f32_e32 v106, v106
	v_pk_mul_f32 v[104:105], v[104:105], v[182:183]
	v_mul_f32_e32 v107, 0x3f317217, v106
	v_fma_f32 v107, v106, s95, -v107
	v_fmac_f32_e32 v107, 0x3377d1cf, v106
	v_fmac_f32_e32 v107, 0x3f317217, v106
	v_cmp_lt_f32_e64 s[46:47], |v106|, s62
	s_nop 1
	v_cndmask_b32_e64 v106, v106, v107, s[46:47]
	v_cndmask_b32_e32 v107, 0, v225, vcc
	v_sub_f32_e32 v181, v106, v107
	v_pk_mul_f32 v[106:107], v[132:133], v[134:135]
	global_store_dwordx4 v[120:121], v[108:111], off
	global_store_dwordx4 v[120:121], v[178:181], off offset:16

.LBB0_360:
	s_andn2_b64 vcc, exec, s[36:37]
	s_cbranch_vccnz .LBB0_362
	v_mul_f32_e32 v104, 0xbfb8aa3b, v118
	v_exp_f32_e32 v104, v104
	v_mul_f32_e32 v129, 0xbfb8aa3b, v121
	v_exp_f32_e32 v129, v129
	v_mul_f32_e32 v133, 0xbfb8aa3b, v117
	v_add_f32_e32 v104, 1.0, v104
	v_rcp_f32_e32 v115, v104
	v_mul_f32_e32 v104, 0x3fb8aa3b, v118
	v_exp_f32_e32 v104, v104
	v_add_f32_e32 v129, 1.0, v129
	v_rcp_f32_e32 v132, v129
	v_exp_f32_e32 v133, v133
	v_add_f32_e32 v104, 1.0, v104
	v_rcp_f32_e32 v124, v104
	v_mul_f32_e32 v104, 0xbfb8aa3b, v119
	v_exp_f32_e32 v104, v104
	v_add_f32_e32 v133, 1.0, v133
	v_rcp_f32_e32 v157, v133
	v_mul_f32_e32 v129, 0x3fb8aa3b, v121
	v_add_f32_e32 v104, 1.0, v104
	v_rcp_f32_e32 v128, v104
	v_mul_f32_e32 v104, 0x3fb8aa3b, v119
	v_exp_f32_e32 v104, v104
	v_mul_f32_e32 v133, 0x3fb8aa3b, v117
	v_exp_f32_e32 v129, v129
	v_exp_f32_e32 v133, v133
	v_add_f32_e32 v104, 1.0, v104
	v_rcp_f32_e32 v125, v104
	v_bfe_u32 v108, v184, 6, 2
	v_bfe_u32 v109, v184, 4, 2
	v_lshlrev_b32_e32 v108, 7, v108
	v_lshl_add_u32 v108, v109, 5, v108
	v_add_u32_e32 v108, 0x21800, v108
	ds_read_b128 v[104:107], v108 offset:16
	ds_read_b128 v[108:111], v108
	v_add_f32_e32 v129, 1.0, v129
	v_add_f32_e32 v133, 1.0, v133
	v_rcp_f32_e32 v129, v129
	v_rcp_f32_e32 v133, v133
	s_waitcnt lgkmcnt(1)
	v_pk_add_f32 v[134:135], v[104:105], 1.0 op_sel_hi:[1,0] neg_lo:[1,0] neg_hi:[1,0]
	s_waitcnt lgkmcnt(0)
	v_pk_add_f32 v[126:127], v[108:109], 1.0 op_sel_hi:[1,0] neg_lo:[1,0] neg_hi:[1,0]
	v_pk_add_f32 v[130:131], v[110:111], 1.0 op_sel_hi:[1,0] neg_lo:[1,0] neg_hi:[1,0]
	v_fma_f32 v108, v115, v126, v108
	v_max_f32_e32 v108, 0xda24260, v108
	v_cmp_gt_f32_e32 vcc, s93, v108
	v_fma_f32 v109, v128, v127, v109
	v_max_f32_e32 v109, 0xda24260, v109
	v_cndmask_b32_e64 v115, 0, 32, vcc
	v_ldexp_f32 v108, v108, v115
	v_log_f32_e32 v108, v108
	v_fmac_f32_e32 v111, v132, v131
	v_max_f32_e32 v111, 0xda24260, v111
	v_pk_add_f32 v[182:183], v[106:107], 1.0 op_sel_hi:[1,0] neg_lo:[1,0] neg_hi:[1,0]
	v_mul_f32_e32 v115, 0x3f317217, v108
	v_fma_f32 v115, v108, s95, -v115
	v_fmac_f32_e32 v115, 0x3377d1cf, v108
	v_fmac_f32_e32 v115, 0x3f317217, v108
	v_cmp_lt_f32_e64 s[46:47], |v108|, s62
	v_mul_f32_e32 v128, 0x3fb8aa3b, v120
	v_mul_f32_e32 v132, 0x3fb8aa3b, v116
	v_cndmask_b32_e64 v108, v108, v115, s[46:47]
	v_cndmask_b32_e32 v115, 0, v225, vcc
	v_cmp_gt_f32_e32 vcc, s93, v109
	v_sub_f32_e32 v108, v108, v115
	v_exp_f32_e32 v128, v128
	v_cndmask_b32_e64 v115, 0, 32, vcc
	v_ldexp_f32 v109, v109, v115
	v_log_f32_e32 v109, v109
	v_exp_f32_e32 v132, v132
	v_add_f32_e32 v128, 1.0, v128
	v_rcp_f32_e32 v128, v128
	v_mul_f32_e32 v115, 0x3f317217, v109
	v_fma_f32 v115, v109, s95, -v115
	v_fmac_f32_e32 v115, 0x3377d1cf, v109
	v_fmac_f32_e32 v115, 0x3f317217, v109
	v_cmp_lt_f32_e64 s[46:47], |v109|, s62
	v_add_f32_e32 v132, 1.0, v132
	v_rcp_f32_e32 v132, v132
	v_cndmask_b32_e64 v109, v109, v115, s[46:47]
	v_cndmask_b32_e32 v115, 0, v225, vcc
	v_sub_f32_e32 v109, v109, v115
	v_mul_f32_e32 v115, 0xbfb8aa3b, v120
	v_exp_f32_e32 v115, v115
	v_pk_mul_f32 v[126:127], v[124:125], v[126:127]
	v_pk_mul_f32 v[124:125], v[128:129], v[130:131]
	v_lshl_add_u64 v[128:129], v[146:147], 0, v[112:113]
	v_add_f32_e32 v115, 1.0, v115
	v_rcp_f32_e32 v115, v115
	s_nop 0
	v_fma_f32 v110, v115, v130, v110
	v_max_f32_e32 v110, 0xda24260, v110
	v_cmp_gt_f32_e32 vcc, s93, v110
	s_nop 1
	v_cndmask_b32_e64 v115, 0, 32, vcc
	v_ldexp_f32 v110, v110, v115
	v_log_f32_e32 v110, v110
	s_nop 0
	v_mul_f32_e32 v115, 0x3f317217, v110
	v_fma_f32 v115, v110, s95, -v115
	v_fmac_f32_e32 v115, 0x3377d1cf, v110
	v_fmac_f32_e32 v115, 0x3f317217, v110
	v_cmp_lt_f32_e64 s[46:47], |v110|, s62
	s_nop 1
	v_cndmask_b32_e64 v110, v110, v115, s[46:47]
	v_cndmask_b32_e32 v115, 0, v225, vcc
	v_cmp_gt_f32_e32 vcc, s93, v111
	v_sub_f32_e32 v110, v110, v115
	s_nop 0
	v_cndmask_b32_e64 v115, 0, 32, vcc
	v_ldexp_f32 v111, v111, v115
	v_log_f32_e32 v111, v111
	s_nop 0
	v_mul_f32_e32 v115, 0x3f317217, v111
	v_fma_f32 v115, v111, s95, -v115
	v_fmac_f32_e32 v115, 0x3377d1cf, v111
	v_fmac_f32_e32 v115, 0x3f317217, v111
	v_cmp_lt_f32_e64 s[46:47], |v111|, s62
	s_nop 1
	v_cndmask_b32_e64 v111, v111, v115, s[46:47]
	v_cndmask_b32_e32 v115, 0, v225, vcc
	v_sub_f32_e32 v111, v111, v115
	v_mul_f32_e32 v115, 0xbfb8aa3b, v116
	v_exp_f32_e32 v115, v115
	s_nop 0
	v_add_f32_e32 v115, 1.0, v115
	v_rcp_f32_e32 v115, v115
	s_nop 0
	v_fma_f32 v104, v115, v134, v104
	v_max_f32_e32 v104, 0xda24260, v104
	v_cmp_gt_f32_e32 vcc, s93, v104
	s_nop 1
	v_cndmask_b32_e64 v115, 0, 32, vcc
	v_ldexp_f32 v104, v104, v115
	v_log_f32_e32 v104, v104
	s_nop 0
	v_mul_f32_e32 v115, 0x3f317217, v104
	v_fma_f32 v115, v104, s95, -v115
	v_fmac_f32_e32 v115, 0x3377d1cf, v104
	v_fmac_f32_e32 v115, 0x3f317217, v104
	v_cmp_lt_f32_e64 s[46:47], |v104|, s62
	s_nop 1
	v_cndmask_b32_e64 v104, v104, v115, s[46:47]
	v_cndmask_b32_e32 v115, 0, v225, vcc
	v_sub_f32_e32 v178, v104, v115
	v_fma_f32 v104, v157, v135, v105
	v_max_f32_e32 v104, 0xda24260, v104
	v_cmp_gt_f32_e32 vcc, s93, v104
	s_nop 1
	v_cndmask_b32_e64 v105, 0, 32, vcc
	v_ldexp_f32 v104, v104, v105
	v_log_f32_e32 v104, v104
	s_nop 0
	v_mul_f32_e32 v105, 0x3f317217, v104
	v_fma_f32 v105, v104, s95, -v105
	v_fmac_f32_e32 v105, 0x3377d1cf, v104
	v_fmac_f32_e32 v105, 0x3f317217, v104
	v_cmp_lt_f32_e64 s[46:47], |v104|, s62
	s_nop 1
	v_cndmask_b32_e64 v104, v104, v105, s[46:47]
	v_cndmask_b32_e32 v105, 0, v225, vcc
	v_sub_f32_e32 v179, v104, v105
	v_mul_f32_e32 v104, 0xbfb8aa3b, v122
	v_exp_f32_e32 v104, v104
	v_mul_f32_e32 v105, 0xbfb8aa3b, v123
	v_exp_f32_e32 v105, v105
	v_add_f32_e32 v104, 1.0, v104
	v_rcp_f32_e32 v115, v104
	v_add_f32_e32 v105, 1.0, v105
	v_rcp_f32_e32 v157, v105
	v_mul_f32_e32 v104, 0x3fb8aa3b, v122
	v_fma_f32 v106, v115, v182, v106
	v_max_f32_e32 v106, 0xda24260, v106
	v_cmp_gt_f32_e32 vcc, s93, v106
	v_fmac_f32_e32 v107, v157, v183
	v_mul_f32_e32 v105, 0x3fb8aa3b, v123
	v_cndmask_b32_e64 v115, 0, 32, vcc
	v_ldexp_f32 v106, v106, v115
	v_log_f32_e32 v106, v106
	v_exp_f32_e32 v104, v104
	v_exp_f32_e32 v105, v105
	v_mul_f32_e32 v115, 0x3f317217, v106
	v_fma_f32 v115, v106, s95, -v115
	v_fmac_f32_e32 v115, 0x3377d1cf, v106
	v_fmac_f32_e32 v115, 0x3f317217, v106
	v_cmp_lt_f32_e64 s[46:47], |v106|, s62
	v_add_f32_e32 v104, 1.0, v104
	v_add_f32_e32 v105, 1.0, v105
	v_cndmask_b32_e64 v106, v106, v115, s[46:47]
	v_cndmask_b32_e32 v115, 0, v225, vcc
	v_sub_f32_e32 v180, v106, v115
	v_max_f32_e32 v106, 0xda24260, v107
	v_cmp_gt_f32_e32 vcc, s93, v106
	v_rcp_f32_e32 v104, v104
	v_rcp_f32_e32 v105, v105
	v_cndmask_b32_e64 v107, 0, 32, vcc
	v_ldexp_f32 v106, v106, v107
	v_log_f32_e32 v106, v106
	v_pk_mul_f32 v[104:105], v[104:105], v[182:183]
	v_mul_f32_e32 v107, 0x3f317217, v106
	v_fma_f32 v107, v106, s95, -v107
	v_fmac_f32_e32 v107, 0x3377d1cf, v106
	v_fmac_f32_e32 v107, 0x3f317217, v106
	v_cmp_lt_f32_e64 s[46:47], |v106|, s62
	s_nop 1
	v_cndmask_b32_e64 v106, v106, v107, s[46:47]
	v_cndmask_b32_e32 v107, 0, v225, vcc
	v_sub_f32_e32 v181, v106, v107
	v_pk_mul_f32 v[106:107], v[132:133], v[134:135]
	global_store_dwordx4 v[128:129], v[108:111], off
	global_store_dwordx4 v[128:129], v[178:181], off offset:16

.LBB0_372:
	s_andn2_b64 vcc, exec, s[36:37]
	s_cbranch_vccnz .LBB0_374
	v_bfe_u32 v100, v184, 6, 2
	v_bfe_u32 v101, v184, 4, 2
	v_lshlrev_b32_e32 v100, 7, v100
	v_lshl_add_u32 v100, v101, 5, v100
	v_add_u32_e32 v100, 0x21800, v100
	ds_read_b128 v[96:99], v100 offset:528
	ds_read_b128 v[100:103], v100 offset:512
	v_mul_f32_e32 v116, 0xbfb8aa3b, v108
	v_exp_f32_e32 v116, v116
	v_mul_f32_e32 v117, 0xbfb8aa3b, v109
	v_exp_f32_e32 v117, v117
	v_lshl_add_u64 v[112:113], v[150:151], 0, v[112:113]
	v_add_f32_e32 v116, 1.0, v116
	v_rcp_f32_e32 v120, v116
	v_add_f32_e32 v117, 1.0, v117
	v_rcp_f32_e32 v121, v117
	v_mul_f32_e32 v116, 0x3fb8aa3b, v108
	v_mul_f32_e32 v117, 0x3fb8aa3b, v109
	v_exp_f32_e32 v116, v116
	v_exp_f32_e32 v117, v117
	v_add_f32_e32 v116, 1.0, v116
	v_add_f32_e32 v117, 1.0, v117
	v_rcp_f32_e32 v116, v116
	v_rcp_f32_e32 v117, v117
	s_waitcnt lgkmcnt(1)
	v_pk_add_f32 v[130:131], v[96:97], 1.0 op_sel_hi:[1,0] neg_lo:[1,0] neg_hi:[1,0]
	s_waitcnt lgkmcnt(0)
	v_pk_add_f32 v[118:119], v[100:101], 1.0 op_sel_hi:[1,0] neg_lo:[1,0] neg_hi:[1,0]
	v_pk_add_f32 v[122:123], v[102:103], 1.0 op_sel_hi:[1,0] neg_lo:[1,0] neg_hi:[1,0]
	v_fma_f32 v100, v120, v118, v100
	v_max_f32_e32 v100, 0xda24260, v100
	v_cmp_gt_f32_e32 vcc, s93, v100
	v_fma_f32 v101, v121, v119, v101
	v_max_f32_e32 v101, 0xda24260, v101
	v_cndmask_b32_e64 v120, 0, 32, vcc
	v_ldexp_f32 v100, v100, v120
	v_log_f32_e32 v100, v100
	v_mul_f32_e32 v121, 0xbfb8aa3b, v111
	v_exp_f32_e32 v121, v121
	v_pk_add_f32 v[132:133], v[98:99], 1.0 op_sel_hi:[1,0] neg_lo:[1,0] neg_hi:[1,0]
	v_mul_f32_e32 v120, 0x3f317217, v100
	v_fma_f32 v120, v100, s95, -v120
	v_fmac_f32_e32 v120, 0x3377d1cf, v100
	v_fmac_f32_e32 v120, 0x3f317217, v100
	v_cmp_lt_f32_e64 s[46:47], |v100|, s62
	v_add_f32_e32 v121, 1.0, v121
	v_rcp_f32_e32 v125, v121
	v_cndmask_b32_e64 v100, v100, v120, s[46:47]
	v_cndmask_b32_e32 v120, 0, v225, vcc
	v_cmp_gt_f32_e32 vcc, s93, v101
	v_sub_f32_e32 v100, v100, v120
	v_fmac_f32_e32 v103, v125, v123
	v_cndmask_b32_e64 v120, 0, 32, vcc
	v_ldexp_f32 v101, v101, v120
	v_log_f32_e32 v101, v101
	v_max_f32_e32 v103, 0xda24260, v103
	v_mul_f32_e32 v125, 0xbfb8aa3b, v107
	v_exp_f32_e32 v125, v125
	v_mul_f32_e32 v120, 0x3f317217, v101
	v_fma_f32 v120, v101, s95, -v120
	v_fmac_f32_e32 v120, 0x3377d1cf, v101
	v_fmac_f32_e32 v120, 0x3f317217, v101
	v_cmp_lt_f32_e64 s[46:47], |v101|, s62
	v_add_f32_e32 v125, 1.0, v125
	v_rcp_f32_e32 v127, v125
	v_cndmask_b32_e64 v101, v101, v120, s[46:47]
	v_cndmask_b32_e32 v120, 0, v225, vcc
	v_sub_f32_e32 v101, v101, v120
	v_mul_f32_e32 v120, 0xbfb8aa3b, v110
	v_exp_f32_e32 v120, v120
	v_mul_f32_e32 v121, 0x3fb8aa3b, v111
	v_mul_f32_e32 v125, 0x3fb8aa3b, v107
	v_exp_f32_e32 v121, v121
	v_add_f32_e32 v120, 1.0, v120
	v_rcp_f32_e32 v124, v120
	v_mul_f32_e32 v120, 0x3fb8aa3b, v110
	v_exp_f32_e32 v120, v120
	v_exp_f32_e32 v125, v125
	v_fma_f32 v102, v124, v122, v102
	v_max_f32_e32 v102, 0xda24260, v102
	v_cmp_gt_f32_e32 vcc, s93, v102
	v_add_f32_e32 v120, 1.0, v120
	v_add_f32_e32 v121, 1.0, v121
	v_cndmask_b32_e64 v124, 0, 32, vcc
	v_ldexp_f32 v102, v102, v124
	v_log_f32_e32 v102, v102
	v_add_f32_e32 v125, 1.0, v125
	v_rcp_f32_e32 v120, v120
	v_rcp_f32_e32 v121, v121
	v_mul_f32_e32 v124, 0x3f317217, v102
	v_fma_f32 v124, v102, s95, -v124
	v_fmac_f32_e32 v124, 0x3377d1cf, v102
	v_fmac_f32_e32 v124, 0x3f317217, v102
	v_cmp_lt_f32_e64 s[46:47], |v102|, s62
	v_rcp_f32_e32 v125, v125
	v_pk_mul_f32 v[118:119], v[116:117], v[118:119]
	v_cndmask_b32_e64 v102, v102, v124, s[46:47]
	v_cndmask_b32_e32 v124, 0, v225, vcc
	v_cmp_gt_f32_e32 vcc, s93, v103
	v_sub_f32_e32 v102, v102, v124
	v_pk_mul_f32 v[116:117], v[120:121], v[122:123]
	v_cndmask_b32_e64 v124, 0, 32, vcc
	v_ldexp_f32 v103, v103, v124
	v_log_f32_e32 v103, v103
	s_nop 0
	v_mul_f32_e32 v124, 0x3f317217, v103
	v_fma_f32 v124, v103, s95, -v124
	v_fmac_f32_e32 v124, 0x3377d1cf, v103
	v_fmac_f32_e32 v124, 0x3f317217, v103
	v_cmp_lt_f32_e64 s[46:47], |v103|, s62
	s_nop 1
	v_cndmask_b32_e64 v103, v103, v124, s[46:47]
	v_cndmask_b32_e32 v124, 0, v225, vcc
	v_sub_f32_e32 v103, v103, v124
	v_mul_f32_e32 v124, 0xbfb8aa3b, v106
	v_exp_f32_e32 v124, v124
	s_nop 0
	v_add_f32_e32 v124, 1.0, v124
	v_rcp_f32_e32 v126, v124
	v_mul_f32_e32 v124, 0x3fb8aa3b, v106
	v_exp_f32_e32 v124, v124
	v_fma_f32 v96, v126, v130, v96
	v_max_f32_e32 v96, 0xda24260, v96
	v_cmp_gt_f32_e32 vcc, s93, v96
	v_add_f32_e32 v124, 1.0, v124
	v_rcp_f32_e32 v124, v124
	v_cndmask_b32_e64 v126, 0, 32, vcc
	v_ldexp_f32 v96, v96, v126
	v_log_f32_e32 v96, v96
	s_nop 0
	v_mul_f32_e32 v126, 0x3f317217, v96
	v_fma_f32 v126, v96, s95, -v126
	v_fmac_f32_e32 v126, 0x3377d1cf, v96
	v_fmac_f32_e32 v126, 0x3f317217, v96
	v_cmp_lt_f32_e64 s[46:47], |v96|, s62
	s_nop 1
	v_cndmask_b32_e64 v96, v96, v126, s[46:47]
	v_cndmask_b32_e32 v126, 0, v225, vcc
	v_sub_f32_e32 v126, v96, v126
	v_fma_f32 v96, v127, v131, v97
	v_max_f32_e32 v96, 0xda24260, v96
	v_cmp_gt_f32_e32 vcc, s93, v96
	s_nop 1
	v_cndmask_b32_e64 v97, 0, 32, vcc
	v_ldexp_f32 v96, v96, v97
	v_log_f32_e32 v96, v96
	s_nop 0
	v_mul_f32_e32 v97, 0x3f317217, v96
	v_fma_f32 v97, v96, s95, -v97
	v_fmac_f32_e32 v97, 0x3377d1cf, v96
	v_fmac_f32_e32 v97, 0x3f317217, v96
	v_cmp_lt_f32_e64 s[46:47], |v96|, s62
	s_nop 1
	v_cndmask_b32_e64 v96, v96, v97, s[46:47]
	v_cndmask_b32_e32 v97, 0, v225, vcc
	v_sub_f32_e32 v127, v96, v97
	v_mul_f32_e32 v96, 0xbfb8aa3b, v114
	v_exp_f32_e32 v96, v96
	v_mul_f32_e32 v97, 0xbfb8aa3b, v115
	v_exp_f32_e32 v97, v97
	v_add_f32_e32 v96, 1.0, v96
	v_rcp_f32_e32 v128, v96
	v_add_f32_e32 v97, 1.0, v97
	v_rcp_f32_e32 v129, v97
	v_mul_f32_e32 v96, 0x3fb8aa3b, v114
	v_fma_f32 v98, v128, v132, v98
	v_max_f32_e32 v98, 0xda24260, v98
	v_cmp_gt_f32_e32 vcc, s93, v98
	v_fmac_f32_e32 v99, v129, v133
	v_mul_f32_e32 v97, 0x3fb8aa3b, v115
	v_cndmask_b32_e64 v128, 0, 32, vcc
	v_ldexp_f32 v98, v98, v128
	v_log_f32_e32 v98, v98
	v_exp_f32_e32 v96, v96
	v_exp_f32_e32 v97, v97
	v_mul_f32_e32 v128, 0x3f317217, v98
	v_fma_f32 v128, v98, s95, -v128
	v_fmac_f32_e32 v128, 0x3377d1cf, v98
	v_fmac_f32_e32 v128, 0x3f317217, v98
	v_cmp_lt_f32_e64 s[46:47], |v98|, s62
	v_add_f32_e32 v96, 1.0, v96
	v_add_f32_e32 v97, 1.0, v97
	v_cndmask_b32_e64 v98, v98, v128, s[46:47]
	v_cndmask_b32_e32 v128, 0, v225, vcc
	v_sub_f32_e32 v128, v98, v128
	v_max_f32_e32 v98, 0xda24260, v99
	v_cmp_gt_f32_e32 vcc, s93, v98
	v_rcp_f32_e32 v96, v96
	v_rcp_f32_e32 v97, v97
	v_cndmask_b32_e64 v99, 0, 32, vcc
	v_ldexp_f32 v98, v98, v99
	v_log_f32_e32 v98, v98
	v_pk_mul_f32 v[96:97], v[96:97], v[132:133]
	v_mul_f32_e32 v99, 0x3f317217, v98
	v_fma_f32 v99, v98, s95, -v99
	v_fmac_f32_e32 v99, 0x3377d1cf, v98
	v_fmac_f32_e32 v99, 0x3f317217, v98
	v_cmp_lt_f32_e64 s[46:47], |v98|, s62
	s_nop 1
	v_cndmask_b32_e64 v98, v98, v99, s[46:47]
	v_cndmask_b32_e32 v99, 0, v225, vcc
	v_sub_f32_e32 v129, v98, v99
	v_pk_mul_f32 v[98:99], v[124:125], v[130:131]
	global_store_dwordx4 v[112:113], v[100:103], off
	global_store_dwordx4 v[112:113], v[126:129], off offset:16

.LBB0_384:
	s_andn2_b64 vcc, exec, s[36:37]
	s_cbranch_vccnz .LBB0_386
	v_mul_f32_e32 v96, 0xbfb8aa3b, v108
	v_exp_f32_e32 v96, v96
	s_nop 0
	v_add_f32_e32 v96, 1.0, v96
	v_rcp_f32_e32 v118, v96
	v_mul_f32_e32 v96, 0x3fb8aa3b, v108
	v_exp_f32_e32 v96, v96
	s_nop 0
	v_add_f32_e32 v96, 1.0, v96
	v_rcp_f32_e32 v114, v96
	v_mul_f32_e32 v96, 0xbfb8aa3b, v109
	v_exp_f32_e32 v96, v96
	s_nop 0
	v_add_f32_e32 v96, 1.0, v96
	v_rcp_f32_e32 v119, v96
	v_mul_f32_e32 v96, 0x3fb8aa3b, v109
	v_exp_f32_e32 v96, v96
	s_nop 0
	v_add_f32_e32 v96, 1.0, v96
	v_rcp_f32_e32 v115, v96
	v_bfe_u32 v100, v184, 6, 2
	v_bfe_u32 v101, v184, 4, 2
	v_lshlrev_b32_e32 v100, 7, v100
	v_lshl_add_u32 v100, v101, 5, v100
	v_add_u32_e32 v100, 0x21800, v100
	ds_read_b128 v[96:99], v100 offset:16
	ds_read_b128 v[100:103], v100
	s_waitcnt lgkmcnt(1)
	v_pk_add_f32 v[128:129], v[96:97], 1.0 op_sel_hi:[1,0] neg_lo:[1,0] neg_hi:[1,0]
	s_waitcnt lgkmcnt(0)
	v_pk_add_f32 v[116:117], v[100:101], 1.0 op_sel_hi:[1,0] neg_lo:[1,0] neg_hi:[1,0]
	v_pk_add_f32 v[120:121], v[102:103], 1.0 op_sel_hi:[1,0] neg_lo:[1,0] neg_hi:[1,0]
	v_fma_f32 v100, v118, v116, v100
	v_max_f32_e32 v100, 0xda24260, v100
	v_cmp_gt_f32_e32 vcc, s93, v100
	v_fma_f32 v101, v119, v117, v101
	v_max_f32_e32 v101, 0xda24260, v101
	v_cndmask_b32_e64 v118, 0, 32, vcc
	v_ldexp_f32 v100, v100, v118
	v_log_f32_e32 v100, v100
	v_mul_f32_e32 v119, 0xbfb8aa3b, v111
	v_exp_f32_e32 v119, v119
	v_pk_add_f32 v[130:131], v[98:99], 1.0 op_sel_hi:[1,0] neg_lo:[1,0] neg_hi:[1,0]
	v_mul_f32_e32 v118, 0x3f317217, v100
	v_fma_f32 v118, v100, s95, -v118
	v_fmac_f32_e32 v118, 0x3377d1cf, v100
	v_fmac_f32_e32 v118, 0x3f317217, v100
	v_cmp_lt_f32_e64 s[46:47], |v100|, s62
	v_add_f32_e32 v119, 1.0, v119
	v_rcp_f32_e32 v123, v119
	v_cndmask_b32_e64 v100, v100, v118, s[46:47]
	v_cndmask_b32_e32 v118, 0, v225, vcc
	v_cmp_gt_f32_e32 vcc, s93, v101
	v_sub_f32_e32 v100, v100, v118
	v_fmac_f32_e32 v103, v123, v121
	v_cndmask_b32_e64 v118, 0, 32, vcc
	v_ldexp_f32 v101, v101, v118
	v_log_f32_e32 v101, v101
	v_max_f32_e32 v103, 0xda24260, v103
	v_mul_f32_e32 v123, 0xbfb8aa3b, v107
	v_exp_f32_e32 v123, v123
	v_mul_f32_e32 v118, 0x3f317217, v101
	v_fma_f32 v118, v101, s95, -v118
	v_fmac_f32_e32 v118, 0x3377d1cf, v101
	v_fmac_f32_e32 v118, 0x3f317217, v101
	v_cmp_lt_f32_e64 s[46:47], |v101|, s62
	v_add_f32_e32 v123, 1.0, v123
	v_rcp_f32_e32 v125, v123
	v_cndmask_b32_e64 v101, v101, v118, s[46:47]
	v_cndmask_b32_e32 v118, 0, v225, vcc
	v_sub_f32_e32 v101, v101, v118
	v_mul_f32_e32 v118, 0xbfb8aa3b, v110
	v_exp_f32_e32 v118, v118
	v_mul_f32_e32 v119, 0x3fb8aa3b, v111
	v_mul_f32_e32 v123, 0x3fb8aa3b, v107
	v_exp_f32_e32 v119, v119
	v_add_f32_e32 v118, 1.0, v118
	v_rcp_f32_e32 v122, v118
	v_mul_f32_e32 v118, 0x3fb8aa3b, v110
	v_exp_f32_e32 v118, v118
	v_exp_f32_e32 v123, v123
	v_fma_f32 v102, v122, v120, v102
	v_max_f32_e32 v102, 0xda24260, v102
	v_cmp_gt_f32_e32 vcc, s93, v102
	v_add_f32_e32 v118, 1.0, v118
	v_add_f32_e32 v119, 1.0, v119
	v_cndmask_b32_e64 v122, 0, 32, vcc
	v_ldexp_f32 v102, v102, v122
	v_log_f32_e32 v102, v102
	v_add_f32_e32 v123, 1.0, v123
	v_rcp_f32_e32 v118, v118
	v_rcp_f32_e32 v119, v119
	v_mul_f32_e32 v122, 0x3f317217, v102
	v_fma_f32 v122, v102, s95, -v122
	v_fmac_f32_e32 v122, 0x3377d1cf, v102
	v_fmac_f32_e32 v122, 0x3f317217, v102
	v_cmp_lt_f32_e64 s[46:47], |v102|, s62
	v_rcp_f32_e32 v123, v123
	v_pk_mul_f32 v[116:117], v[114:115], v[116:117]
	v_cndmask_b32_e64 v102, v102, v122, s[46:47]
	v_cndmask_b32_e32 v122, 0, v225, vcc
	v_cmp_gt_f32_e32 vcc, s93, v103
	v_sub_f32_e32 v102, v102, v122
	v_pk_mul_f32 v[114:115], v[118:119], v[120:121]
	v_cndmask_b32_e64 v122, 0, 32, vcc
	v_ldexp_f32 v103, v103, v122
	v_log_f32_e32 v103, v103
	v_lshl_add_u64 v[118:119], v[146:147], 0, v[104:105]
	v_mul_f32_e32 v122, 0x3f317217, v103
	v_fma_f32 v122, v103, s95, -v122
	v_fmac_f32_e32 v122, 0x3377d1cf, v103
	v_fmac_f32_e32 v122, 0x3f317217, v103
	v_cmp_lt_f32_e64 s[46:47], |v103|, s62
	s_nop 1
	v_cndmask_b32_e64 v103, v103, v122, s[46:47]
	v_cndmask_b32_e32 v122, 0, v225, vcc
	v_sub_f32_e32 v103, v103, v122
	v_mul_f32_e32 v122, 0xbfb8aa3b, v106
	v_exp_f32_e32 v122, v122
	s_nop 0
	v_add_f32_e32 v122, 1.0, v122
	v_rcp_f32_e32 v124, v122
	v_mul_f32_e32 v122, 0x3fb8aa3b, v106
	v_exp_f32_e32 v122, v122
	v_fma_f32 v96, v124, v128, v96
	v_max_f32_e32 v96, 0xda24260, v96
	v_cmp_gt_f32_e32 vcc, s93, v96
	v_add_f32_e32 v122, 1.0, v122
	v_rcp_f32_e32 v122, v122
	v_cndmask_b32_e64 v124, 0, 32, vcc
	v_ldexp_f32 v96, v96, v124
	v_log_f32_e32 v96, v96
	s_nop 0
	v_mul_f32_e32 v124, 0x3f317217, v96
	v_fma_f32 v124, v96, s95, -v124
	v_fmac_f32_e32 v124, 0x3377d1cf, v96
	v_fmac_f32_e32 v124, 0x3f317217, v96
	v_cmp_lt_f32_e64 s[46:47], |v96|, s62
	s_nop 1
	v_cndmask_b32_e64 v96, v96, v124, s[46:47]
	v_cndmask_b32_e32 v124, 0, v225, vcc
	v_sub_f32_e32 v124, v96, v124
	v_fma_f32 v96, v125, v129, v97
	v_max_f32_e32 v96, 0xda24260, v96
	v_cmp_gt_f32_e32 vcc, s93, v96
	s_nop 1
	v_cndmask_b32_e64 v97, 0, 32, vcc
	v_ldexp_f32 v96, v96, v97
	v_log_f32_e32 v96, v96
	s_nop 0
	v_mul_f32_e32 v97, 0x3f317217, v96
	v_fma_f32 v97, v96, s95, -v97
	v_fmac_f32_e32 v97, 0x3377d1cf, v96
	v_fmac_f32_e32 v97, 0x3f317217, v96
	v_cmp_lt_f32_e64 s[46:47], |v96|, s62
	s_nop 1
	v_cndmask_b32_e64 v96, v96, v97, s[46:47]
	v_cndmask_b32_e32 v97, 0, v225, vcc
	v_sub_f32_e32 v125, v96, v97
	v_mul_f32_e32 v96, 0xbfb8aa3b, v112
	v_exp_f32_e32 v96, v96
	v_mul_f32_e32 v97, 0xbfb8aa3b, v113
	v_exp_f32_e32 v97, v97
	v_add_f32_e32 v96, 1.0, v96
	v_rcp_f32_e32 v126, v96
	v_add_f32_e32 v97, 1.0, v97
	v_rcp_f32_e32 v127, v97
	v_mul_f32_e32 v96, 0x3fb8aa3b, v112
	v_fma_f32 v98, v126, v130, v98
	v_max_f32_e32 v98, 0xda24260, v98
	v_cmp_gt_f32_e32 vcc, s93, v98
	v_fmac_f32_e32 v99, v127, v131
	v_mul_f32_e32 v97, 0x3fb8aa3b, v113
	v_cndmask_b32_e64 v126, 0, 32, vcc
	v_ldexp_f32 v98, v98, v126
	v_log_f32_e32 v98, v98
	v_exp_f32_e32 v96, v96
	v_exp_f32_e32 v97, v97
	v_mul_f32_e32 v126, 0x3f317217, v98
	v_fma_f32 v126, v98, s95, -v126
	v_fmac_f32_e32 v126, 0x3377d1cf, v98
	v_fmac_f32_e32 v126, 0x3f317217, v98
	v_cmp_lt_f32_e64 s[46:47], |v98|, s62
	v_add_f32_e32 v96, 1.0, v96
	v_add_f32_e32 v97, 1.0, v97
	v_cndmask_b32_e64 v98, v98, v126, s[46:47]
	v_cndmask_b32_e32 v126, 0, v225, vcc
	v_sub_f32_e32 v126, v98, v126
	v_max_f32_e32 v98, 0xda24260, v99
	v_cmp_gt_f32_e32 vcc, s93, v98
	v_rcp_f32_e32 v96, v96
	v_rcp_f32_e32 v97, v97
	v_cndmask_b32_e64 v99, 0, 32, vcc
	v_ldexp_f32 v98, v98, v99
	v_log_f32_e32 v98, v98
	v_pk_mul_f32 v[96:97], v[96:97], v[130:131]
	v_mul_f32_e32 v99, 0x3f317217, v98
	v_fma_f32 v99, v98, s95, -v99
	v_fmac_f32_e32 v99, 0x3377d1cf, v98
	v_fmac_f32_e32 v99, 0x3f317217, v98
	v_cmp_lt_f32_e64 s[46:47], |v98|, s62
	s_nop 1
	v_cndmask_b32_e64 v98, v98, v99, s[46:47]
	v_cndmask_b32_e32 v99, 0, v225, vcc
	v_sub_f32_e32 v127, v98, v99
	v_pk_mul_f32 v[98:99], v[122:123], v[128:129]
	global_store_dwordx4 v[118:119], v[100:103], off
	global_store_dwordx4 v[118:119], v[124:127], off offset:16

.LBB0_396:
	s_andn2_b64 vcc, exec, s[36:37]
	s_cbranch_vccnz .LBB0_398
	v_bfe_u32 v92, v184, 6, 2
	v_bfe_u32 v93, v184, 4, 2
	v_lshlrev_b32_e32 v92, 7, v92
	v_lshl_add_u32 v92, v93, 5, v92
	v_add_u32_e32 v92, 0x21800, v92
	ds_read_b128 v[88:91], v92 offset:528
	ds_read_b128 v[92:95], v92 offset:512
	v_mul_f32_e32 v108, 0xbfb8aa3b, v100
	v_exp_f32_e32 v108, v108
	v_mul_f32_e32 v109, 0xbfb8aa3b, v101
	v_exp_f32_e32 v109, v109
	v_lshl_add_u64 v[104:105], v[150:151], 0, v[104:105]
	v_add_f32_e32 v108, 1.0, v108
	v_rcp_f32_e32 v112, v108
	v_add_f32_e32 v109, 1.0, v109
	v_rcp_f32_e32 v113, v109
	v_mul_f32_e32 v108, 0x3fb8aa3b, v100
	v_mul_f32_e32 v109, 0x3fb8aa3b, v101
	v_exp_f32_e32 v108, v108
	v_exp_f32_e32 v109, v109
	v_add_f32_e32 v108, 1.0, v108
	v_add_f32_e32 v109, 1.0, v109
	v_rcp_f32_e32 v108, v108
	v_rcp_f32_e32 v109, v109
	s_waitcnt lgkmcnt(1)
	v_pk_add_f32 v[122:123], v[88:89], 1.0 op_sel_hi:[1,0] neg_lo:[1,0] neg_hi:[1,0]
	s_waitcnt lgkmcnt(0)
	v_pk_add_f32 v[110:111], v[92:93], 1.0 op_sel_hi:[1,0] neg_lo:[1,0] neg_hi:[1,0]
	v_pk_add_f32 v[114:115], v[94:95], 1.0 op_sel_hi:[1,0] neg_lo:[1,0] neg_hi:[1,0]
	v_fma_f32 v92, v112, v110, v92
	v_max_f32_e32 v92, 0xda24260, v92
	v_cmp_gt_f32_e32 vcc, s93, v92
	v_fma_f32 v93, v113, v111, v93
	v_max_f32_e32 v93, 0xda24260, v93
	v_cndmask_b32_e64 v112, 0, 32, vcc
	v_ldexp_f32 v92, v92, v112
	v_log_f32_e32 v92, v92
	v_mul_f32_e32 v113, 0xbfb8aa3b, v103
	v_exp_f32_e32 v113, v113
	v_pk_add_f32 v[124:125], v[90:91], 1.0 op_sel_hi:[1,0] neg_lo:[1,0] neg_hi:[1,0]
	v_mul_f32_e32 v112, 0x3f317217, v92
	v_fma_f32 v112, v92, s95, -v112
	v_fmac_f32_e32 v112, 0x3377d1cf, v92
	v_fmac_f32_e32 v112, 0x3f317217, v92
	v_cmp_lt_f32_e64 s[46:47], |v92|, s62
	v_add_f32_e32 v113, 1.0, v113
	v_rcp_f32_e32 v117, v113
	v_cndmask_b32_e64 v92, v92, v112, s[46:47]
	v_cndmask_b32_e32 v112, 0, v225, vcc
	v_cmp_gt_f32_e32 vcc, s93, v93
	v_sub_f32_e32 v92, v92, v112
	v_fmac_f32_e32 v95, v117, v115
	v_cndmask_b32_e64 v112, 0, 32, vcc
	v_ldexp_f32 v93, v93, v112
	v_log_f32_e32 v93, v93
	v_max_f32_e32 v95, 0xda24260, v95
	v_mul_f32_e32 v117, 0xbfb8aa3b, v99
	v_exp_f32_e32 v117, v117
	v_mul_f32_e32 v112, 0x3f317217, v93
	v_fma_f32 v112, v93, s95, -v112
	v_fmac_f32_e32 v112, 0x3377d1cf, v93
	v_fmac_f32_e32 v112, 0x3f317217, v93
	v_cmp_lt_f32_e64 s[46:47], |v93|, s62
	v_add_f32_e32 v117, 1.0, v117
	v_rcp_f32_e32 v119, v117
	v_cndmask_b32_e64 v93, v93, v112, s[46:47]
	v_cndmask_b32_e32 v112, 0, v225, vcc
	v_sub_f32_e32 v93, v93, v112
	v_mul_f32_e32 v112, 0xbfb8aa3b, v102
	v_exp_f32_e32 v112, v112
	v_mul_f32_e32 v113, 0x3fb8aa3b, v103
	v_mul_f32_e32 v117, 0x3fb8aa3b, v99
	v_exp_f32_e32 v113, v113
	v_add_f32_e32 v112, 1.0, v112
	v_rcp_f32_e32 v116, v112
	v_mul_f32_e32 v112, 0x3fb8aa3b, v102
	v_exp_f32_e32 v112, v112
	v_exp_f32_e32 v117, v117
	v_fma_f32 v94, v116, v114, v94
	v_max_f32_e32 v94, 0xda24260, v94
	v_cmp_gt_f32_e32 vcc, s93, v94
	v_add_f32_e32 v112, 1.0, v112
	v_add_f32_e32 v113, 1.0, v113
	v_cndmask_b32_e64 v116, 0, 32, vcc
	v_ldexp_f32 v94, v94, v116
	v_log_f32_e32 v94, v94
	v_add_f32_e32 v117, 1.0, v117
	v_rcp_f32_e32 v112, v112
	v_rcp_f32_e32 v113, v113
	v_mul_f32_e32 v116, 0x3f317217, v94
	v_fma_f32 v116, v94, s95, -v116
	v_fmac_f32_e32 v116, 0x3377d1cf, v94
	v_fmac_f32_e32 v116, 0x3f317217, v94
	v_cmp_lt_f32_e64 s[46:47], |v94|, s62
	v_rcp_f32_e32 v117, v117
	v_pk_mul_f32 v[110:111], v[108:109], v[110:111]
	v_cndmask_b32_e64 v94, v94, v116, s[46:47]
	v_cndmask_b32_e32 v116, 0, v225, vcc
	v_cmp_gt_f32_e32 vcc, s93, v95
	v_sub_f32_e32 v94, v94, v116
	v_pk_mul_f32 v[108:109], v[112:113], v[114:115]
	v_cndmask_b32_e64 v116, 0, 32, vcc
	v_ldexp_f32 v95, v95, v116
	v_log_f32_e32 v95, v95
	s_nop 0
	v_mul_f32_e32 v116, 0x3f317217, v95
	v_fma_f32 v116, v95, s95, -v116
	v_fmac_f32_e32 v116, 0x3377d1cf, v95
	v_fmac_f32_e32 v116, 0x3f317217, v95
	v_cmp_lt_f32_e64 s[46:47], |v95|, s62
	s_nop 1
	v_cndmask_b32_e64 v95, v95, v116, s[46:47]
	v_cndmask_b32_e32 v116, 0, v225, vcc
	v_sub_f32_e32 v95, v95, v116
	v_mul_f32_e32 v116, 0xbfb8aa3b, v98
	v_exp_f32_e32 v116, v116
	s_nop 0
	v_add_f32_e32 v116, 1.0, v116
	v_rcp_f32_e32 v118, v116
	v_mul_f32_e32 v116, 0x3fb8aa3b, v98
	v_exp_f32_e32 v116, v116
	v_fma_f32 v88, v118, v122, v88
	v_max_f32_e32 v88, 0xda24260, v88
	v_cmp_gt_f32_e32 vcc, s93, v88
	v_add_f32_e32 v116, 1.0, v116
	v_rcp_f32_e32 v116, v116
	v_cndmask_b32_e64 v118, 0, 32, vcc
	v_ldexp_f32 v88, v88, v118
	v_log_f32_e32 v88, v88
	s_nop 0
	v_mul_f32_e32 v118, 0x3f317217, v88
	v_fma_f32 v118, v88, s95, -v118
	v_fmac_f32_e32 v118, 0x3377d1cf, v88
	v_fmac_f32_e32 v118, 0x3f317217, v88
	v_cmp_lt_f32_e64 s[46:47], |v88|, s62
	s_nop 1
	v_cndmask_b32_e64 v88, v88, v118, s[46:47]
	v_cndmask_b32_e32 v118, 0, v225, vcc
	v_sub_f32_e32 v118, v88, v118
	v_fma_f32 v88, v119, v123, v89
	v_max_f32_e32 v88, 0xda24260, v88
	v_cmp_gt_f32_e32 vcc, s93, v88
	s_nop 1
	v_cndmask_b32_e64 v89, 0, 32, vcc
	v_ldexp_f32 v88, v88, v89
	v_log_f32_e32 v88, v88
	s_nop 0
	v_mul_f32_e32 v89, 0x3f317217, v88
	v_fma_f32 v89, v88, s95, -v89
	v_fmac_f32_e32 v89, 0x3377d1cf, v88
	v_fmac_f32_e32 v89, 0x3f317217, v88
	v_cmp_lt_f32_e64 s[46:47], |v88|, s62
	s_nop 1
	v_cndmask_b32_e64 v88, v88, v89, s[46:47]
	v_cndmask_b32_e32 v89, 0, v225, vcc
	v_sub_f32_e32 v119, v88, v89
	v_mul_f32_e32 v88, 0xbfb8aa3b, v106
	v_exp_f32_e32 v88, v88
	v_mul_f32_e32 v89, 0xbfb8aa3b, v107
	v_exp_f32_e32 v89, v89
	v_add_f32_e32 v88, 1.0, v88
	v_rcp_f32_e32 v120, v88
	v_add_f32_e32 v89, 1.0, v89
	v_rcp_f32_e32 v121, v89
	v_mul_f32_e32 v88, 0x3fb8aa3b, v106
	v_fma_f32 v90, v120, v124, v90
	v_max_f32_e32 v90, 0xda24260, v90
	v_cmp_gt_f32_e32 vcc, s93, v90
	v_fmac_f32_e32 v91, v121, v125
	v_mul_f32_e32 v89, 0x3fb8aa3b, v107
	v_cndmask_b32_e64 v120, 0, 32, vcc
	v_ldexp_f32 v90, v90, v120
	v_log_f32_e32 v90, v90
	v_exp_f32_e32 v88, v88
	v_exp_f32_e32 v89, v89
	v_mul_f32_e32 v120, 0x3f317217, v90
	v_fma_f32 v120, v90, s95, -v120
	v_fmac_f32_e32 v120, 0x3377d1cf, v90
	v_fmac_f32_e32 v120, 0x3f317217, v90
	v_cmp_lt_f32_e64 s[46:47], |v90|, s62
	v_add_f32_e32 v88, 1.0, v88
	v_add_f32_e32 v89, 1.0, v89
	v_cndmask_b32_e64 v90, v90, v120, s[46:47]
	v_cndmask_b32_e32 v120, 0, v225, vcc
	v_sub_f32_e32 v120, v90, v120
	v_max_f32_e32 v90, 0xda24260, v91
	v_cmp_gt_f32_e32 vcc, s93, v90
	v_rcp_f32_e32 v88, v88
	v_rcp_f32_e32 v89, v89
	v_cndmask_b32_e64 v91, 0, 32, vcc
	v_ldexp_f32 v90, v90, v91
	v_log_f32_e32 v90, v90
	v_pk_mul_f32 v[88:89], v[88:89], v[124:125]
	v_mul_f32_e32 v91, 0x3f317217, v90
	v_fma_f32 v91, v90, s95, -v91
	v_fmac_f32_e32 v91, 0x3377d1cf, v90
	v_fmac_f32_e32 v91, 0x3f317217, v90
	v_cmp_lt_f32_e64 s[46:47], |v90|, s62
	s_nop 1
	v_cndmask_b32_e64 v90, v90, v91, s[46:47]
	v_cndmask_b32_e32 v91, 0, v225, vcc
	v_sub_f32_e32 v121, v90, v91
	v_pk_mul_f32 v[90:91], v[116:117], v[122:123]
	global_store_dwordx4 v[104:105], v[92:95], off
	global_store_dwordx4 v[104:105], v[118:121], off offset:16

.LBB0_408:
	s_andn2_b64 vcc, exec, s[36:37]
	s_cbranch_vccnz .LBB0_410
	v_mul_f32_e32 v88, 0xbfb8aa3b, v102
	v_exp_f32_e32 v88, v88
	v_mul_f32_e32 v113, 0xbfb8aa3b, v105
	v_exp_f32_e32 v113, v113
	v_mul_f32_e32 v117, 0xbfb8aa3b, v101
	v_add_f32_e32 v88, 1.0, v88
	v_rcp_f32_e32 v99, v88
	v_mul_f32_e32 v88, 0x3fb8aa3b, v102
	v_exp_f32_e32 v88, v88
	v_add_f32_e32 v113, 1.0, v113
	v_rcp_f32_e32 v116, v113
	v_exp_f32_e32 v117, v117
	v_add_f32_e32 v88, 1.0, v88
	v_rcp_f32_e32 v108, v88
	v_mul_f32_e32 v88, 0xbfb8aa3b, v103
	v_exp_f32_e32 v88, v88
	v_add_f32_e32 v117, 1.0, v117
	v_rcp_f32_e32 v119, v117
	v_mul_f32_e32 v113, 0x3fb8aa3b, v105
	v_add_f32_e32 v88, 1.0, v88
	v_rcp_f32_e32 v112, v88
	v_mul_f32_e32 v88, 0x3fb8aa3b, v103
	v_exp_f32_e32 v88, v88
	v_mul_f32_e32 v117, 0x3fb8aa3b, v101
	v_exp_f32_e32 v113, v113
	v_exp_f32_e32 v117, v117
	v_add_f32_e32 v88, 1.0, v88
	v_rcp_f32_e32 v109, v88
	v_bfe_u32 v92, v184, 6, 2
	v_bfe_u32 v93, v184, 4, 2
	v_lshlrev_b32_e32 v92, 7, v92
	v_lshl_add_u32 v92, v93, 5, v92
	v_add_u32_e32 v92, 0x21800, v92
	ds_read_b128 v[88:91], v92 offset:16
	ds_read_b128 v[92:95], v92
	v_add_f32_e32 v113, 1.0, v113
	v_add_f32_e32 v117, 1.0, v117
	v_rcp_f32_e32 v113, v113
	v_rcp_f32_e32 v117, v117
	s_waitcnt lgkmcnt(1)
	v_pk_add_f32 v[122:123], v[88:89], 1.0 op_sel_hi:[1,0] neg_lo:[1,0] neg_hi:[1,0]
	s_waitcnt lgkmcnt(0)
	v_pk_add_f32 v[110:111], v[92:93], 1.0 op_sel_hi:[1,0] neg_lo:[1,0] neg_hi:[1,0]
	v_pk_add_f32 v[114:115], v[94:95], 1.0 op_sel_hi:[1,0] neg_lo:[1,0] neg_hi:[1,0]
	v_fma_f32 v92, v99, v110, v92
	v_max_f32_e32 v92, 0xda24260, v92
	v_cmp_gt_f32_e32 vcc, s93, v92
	v_fma_f32 v93, v112, v111, v93
	v_max_f32_e32 v93, 0xda24260, v93
	v_cndmask_b32_e64 v99, 0, 32, vcc
	v_ldexp_f32 v92, v92, v99
	v_log_f32_e32 v92, v92
	v_fmac_f32_e32 v95, v116, v115
	v_max_f32_e32 v95, 0xda24260, v95
	v_pk_add_f32 v[124:125], v[90:91], 1.0 op_sel_hi:[1,0] neg_lo:[1,0] neg_hi:[1,0]
	v_mul_f32_e32 v99, 0x3f317217, v92
	v_fma_f32 v99, v92, s95, -v99
	v_fmac_f32_e32 v99, 0x3377d1cf, v92
	v_fmac_f32_e32 v99, 0x3f317217, v92
	v_cmp_lt_f32_e64 s[46:47], |v92|, s62
	v_mul_f32_e32 v112, 0x3fb8aa3b, v104
	v_mul_f32_e32 v116, 0x3fb8aa3b, v100
	v_cndmask_b32_e64 v92, v92, v99, s[46:47]
	v_cndmask_b32_e32 v99, 0, v225, vcc
	v_cmp_gt_f32_e32 vcc, s93, v93
	v_sub_f32_e32 v92, v92, v99
	v_exp_f32_e32 v112, v112
	v_cndmask_b32_e64 v99, 0, 32, vcc
	v_ldexp_f32 v93, v93, v99
	v_log_f32_e32 v93, v93
	v_exp_f32_e32 v116, v116
	v_add_f32_e32 v112, 1.0, v112
	v_rcp_f32_e32 v112, v112
	v_mul_f32_e32 v99, 0x3f317217, v93
	v_fma_f32 v99, v93, s95, -v99
	v_fmac_f32_e32 v99, 0x3377d1cf, v93
	v_fmac_f32_e32 v99, 0x3f317217, v93
	v_cmp_lt_f32_e64 s[46:47], |v93|, s62
	v_add_f32_e32 v116, 1.0, v116
	v_rcp_f32_e32 v116, v116
	v_cndmask_b32_e64 v93, v93, v99, s[46:47]
	v_cndmask_b32_e32 v99, 0, v225, vcc
	v_sub_f32_e32 v93, v93, v99
	v_mul_f32_e32 v99, 0xbfb8aa3b, v104
	v_exp_f32_e32 v99, v99
	v_pk_mul_f32 v[110:111], v[108:109], v[110:111]
	v_pk_mul_f32 v[108:109], v[112:113], v[114:115]
	v_lshl_add_u64 v[112:113], v[146:147], 0, v[96:97]
	v_add_f32_e32 v99, 1.0, v99
	v_rcp_f32_e32 v99, v99
	s_nop 0
	v_fma_f32 v94, v99, v114, v94
	v_max_f32_e32 v94, 0xda24260, v94
	v_cmp_gt_f32_e32 vcc, s93, v94
	s_nop 1
	v_cndmask_b32_e64 v99, 0, 32, vcc
	v_ldexp_f32 v94, v94, v99
	v_log_f32_e32 v94, v94
	s_nop 0
	v_mul_f32_e32 v99, 0x3f317217, v94
	v_fma_f32 v99, v94, s95, -v99
	v_fmac_f32_e32 v99, 0x3377d1cf, v94
	v_fmac_f32_e32 v99, 0x3f317217, v94
	v_cmp_lt_f32_e64 s[46:47], |v94|, s62
	s_nop 1
	v_cndmask_b32_e64 v94, v94, v99, s[46:47]
	v_cndmask_b32_e32 v99, 0, v225, vcc
	v_cmp_gt_f32_e32 vcc, s93, v95
	v_sub_f32_e32 v94, v94, v99
	s_nop 0
	v_cndmask_b32_e64 v99, 0, 32, vcc
	v_ldexp_f32 v95, v95, v99
	v_log_f32_e32 v95, v95
	s_nop 0
	v_mul_f32_e32 v99, 0x3f317217, v95
	v_fma_f32 v99, v95, s95, -v99
	v_fmac_f32_e32 v99, 0x3377d1cf, v95
	v_fmac_f32_e32 v99, 0x3f317217, v95
	v_cmp_lt_f32_e64 s[46:47], |v95|, s62
	s_nop 1
	v_cndmask_b32_e64 v95, v95, v99, s[46:47]
	v_cndmask_b32_e32 v99, 0, v225, vcc
	v_sub_f32_e32 v95, v95, v99
	v_mul_f32_e32 v99, 0xbfb8aa3b, v100
	v_exp_f32_e32 v99, v99
	s_nop 0
	v_add_f32_e32 v99, 1.0, v99
	v_rcp_f32_e32 v99, v99
	s_nop 0
	v_fma_f32 v88, v99, v122, v88
	v_max_f32_e32 v88, 0xda24260, v88
	v_cmp_gt_f32_e32 vcc, s93, v88
	s_nop 1
	v_cndmask_b32_e64 v99, 0, 32, vcc
	v_ldexp_f32 v88, v88, v99
	v_log_f32_e32 v88, v88
	s_nop 0
	v_mul_f32_e32 v99, 0x3f317217, v88
	v_fma_f32 v99, v88, s95, -v99
	v_fmac_f32_e32 v99, 0x3377d1cf, v88
	v_fmac_f32_e32 v99, 0x3f317217, v88
	v_cmp_lt_f32_e64 s[46:47], |v88|, s62
	s_nop 1
	v_cndmask_b32_e64 v88, v88, v99, s[46:47]
	v_cndmask_b32_e32 v99, 0, v225, vcc
	v_sub_f32_e32 v118, v88, v99
	v_fma_f32 v88, v119, v123, v89
	v_max_f32_e32 v88, 0xda24260, v88
	v_cmp_gt_f32_e32 vcc, s93, v88
	s_nop 1
	v_cndmask_b32_e64 v89, 0, 32, vcc
	v_ldexp_f32 v88, v88, v89
	v_log_f32_e32 v88, v88
	s_nop 0
	v_mul_f32_e32 v89, 0x3f317217, v88
	v_fma_f32 v89, v88, s95, -v89
	v_fmac_f32_e32 v89, 0x3377d1cf, v88
	v_fmac_f32_e32 v89, 0x3f317217, v88
	v_cmp_lt_f32_e64 s[46:47], |v88|, s62
	s_nop 1
	v_cndmask_b32_e64 v88, v88, v89, s[46:47]
	v_cndmask_b32_e32 v89, 0, v225, vcc
	v_sub_f32_e32 v119, v88, v89
	v_mul_f32_e32 v88, 0xbfb8aa3b, v106
	v_exp_f32_e32 v88, v88
	v_mul_f32_e32 v89, 0xbfb8aa3b, v107
	v_exp_f32_e32 v89, v89
	v_add_f32_e32 v88, 1.0, v88
	v_rcp_f32_e32 v99, v88
	v_add_f32_e32 v89, 1.0, v89
	v_rcp_f32_e32 v121, v89
	v_mul_f32_e32 v88, 0x3fb8aa3b, v106
	v_fma_f32 v90, v99, v124, v90
	v_max_f32_e32 v90, 0xda24260, v90
	v_cmp_gt_f32_e32 vcc, s93, v90
	v_fmac_f32_e32 v91, v121, v125
	v_mul_f32_e32 v89, 0x3fb8aa3b, v107
	v_cndmask_b32_e64 v99, 0, 32, vcc
	v_ldexp_f32 v90, v90, v99
	v_log_f32_e32 v90, v90
	v_exp_f32_e32 v88, v88
	v_exp_f32_e32 v89, v89
	v_mul_f32_e32 v99, 0x3f317217, v90
	v_fma_f32 v99, v90, s95, -v99
	v_fmac_f32_e32 v99, 0x3377d1cf, v90
	v_fmac_f32_e32 v99, 0x3f317217, v90
	v_cmp_lt_f32_e64 s[46:47], |v90|, s62
	v_add_f32_e32 v88, 1.0, v88
	v_add_f32_e32 v89, 1.0, v89
	v_cndmask_b32_e64 v90, v90, v99, s[46:47]
	v_cndmask_b32_e32 v99, 0, v225, vcc
	v_sub_f32_e32 v120, v90, v99
	v_max_f32_e32 v90, 0xda24260, v91
	v_cmp_gt_f32_e32 vcc, s93, v90
	v_rcp_f32_e32 v88, v88
	v_rcp_f32_e32 v89, v89
	v_cndmask_b32_e64 v91, 0, 32, vcc
	v_ldexp_f32 v90, v90, v91
	v_log_f32_e32 v90, v90
	v_pk_mul_f32 v[88:89], v[88:89], v[124:125]
	v_mul_f32_e32 v91, 0x3f317217, v90
	v_fma_f32 v91, v90, s95, -v91
	v_fmac_f32_e32 v91, 0x3377d1cf, v90
	v_fmac_f32_e32 v91, 0x3f317217, v90
	v_cmp_lt_f32_e64 s[46:47], |v90|, s62
	s_nop 1
	v_cndmask_b32_e64 v90, v90, v91, s[46:47]
	v_cndmask_b32_e32 v91, 0, v225, vcc
	v_sub_f32_e32 v121, v90, v91
	v_pk_mul_f32 v[90:91], v[116:117], v[122:123]
	global_store_dwordx4 v[112:113], v[92:95], off
	global_store_dwordx4 v[112:113], v[118:121], off offset:16

.LBB0_420:
	s_andn2_b64 vcc, exec, s[36:37]
	s_cbranch_vccnz .LBB0_422
	v_bfe_u32 v84, v184, 6, 2
	v_bfe_u32 v85, v184, 4, 2
	v_lshlrev_b32_e32 v84, 7, v84
	v_lshl_add_u32 v84, v85, 5, v84
	v_add_u32_e32 v84, 0x21800, v84
	ds_read_b128 v[80:83], v84 offset:528
	ds_read_b128 v[84:87], v84 offset:512
	v_mul_f32_e32 v100, 0xbfb8aa3b, v92
	v_exp_f32_e32 v100, v100
	v_mul_f32_e32 v101, 0xbfb8aa3b, v93
	v_exp_f32_e32 v101, v101
	v_lshl_add_u64 v[96:97], v[150:151], 0, v[96:97]
	v_add_f32_e32 v100, 1.0, v100
	v_rcp_f32_e32 v104, v100
	v_add_f32_e32 v101, 1.0, v101
	v_rcp_f32_e32 v105, v101
	v_mul_f32_e32 v100, 0x3fb8aa3b, v92
	v_mul_f32_e32 v101, 0x3fb8aa3b, v93
	v_exp_f32_e32 v100, v100
	v_exp_f32_e32 v101, v101
	v_add_f32_e32 v100, 1.0, v100
	v_add_f32_e32 v101, 1.0, v101
	v_rcp_f32_e32 v100, v100
	v_rcp_f32_e32 v101, v101
	s_waitcnt lgkmcnt(1)
	v_pk_add_f32 v[114:115], v[80:81], 1.0 op_sel_hi:[1,0] neg_lo:[1,0] neg_hi:[1,0]
	s_waitcnt lgkmcnt(0)
	v_pk_add_f32 v[102:103], v[84:85], 1.0 op_sel_hi:[1,0] neg_lo:[1,0] neg_hi:[1,0]
	v_pk_add_f32 v[106:107], v[86:87], 1.0 op_sel_hi:[1,0] neg_lo:[1,0] neg_hi:[1,0]
	v_fma_f32 v84, v104, v102, v84
	v_max_f32_e32 v84, 0xda24260, v84
	v_cmp_gt_f32_e32 vcc, s93, v84
	v_fma_f32 v85, v105, v103, v85
	v_max_f32_e32 v85, 0xda24260, v85
	v_cndmask_b32_e64 v104, 0, 32, vcc
	v_ldexp_f32 v84, v84, v104
	v_log_f32_e32 v84, v84
	v_mul_f32_e32 v105, 0xbfb8aa3b, v95
	v_exp_f32_e32 v105, v105
	v_pk_add_f32 v[116:117], v[82:83], 1.0 op_sel_hi:[1,0] neg_lo:[1,0] neg_hi:[1,0]
	v_mul_f32_e32 v104, 0x3f317217, v84
	v_fma_f32 v104, v84, s95, -v104
	v_fmac_f32_e32 v104, 0x3377d1cf, v84
	v_fmac_f32_e32 v104, 0x3f317217, v84
	v_cmp_lt_f32_e64 s[46:47], |v84|, s62
	v_add_f32_e32 v105, 1.0, v105
	v_rcp_f32_e32 v109, v105
	v_cndmask_b32_e64 v84, v84, v104, s[46:47]
	v_cndmask_b32_e32 v104, 0, v225, vcc
	v_cmp_gt_f32_e32 vcc, s93, v85
	v_sub_f32_e32 v84, v84, v104
	v_fmac_f32_e32 v87, v109, v107
	v_cndmask_b32_e64 v104, 0, 32, vcc
	v_ldexp_f32 v85, v85, v104
	v_log_f32_e32 v85, v85
	v_max_f32_e32 v87, 0xda24260, v87
	v_mul_f32_e32 v109, 0xbfb8aa3b, v91
	v_exp_f32_e32 v109, v109
	v_mul_f32_e32 v104, 0x3f317217, v85
	v_fma_f32 v104, v85, s95, -v104
	v_fmac_f32_e32 v104, 0x3377d1cf, v85
	v_fmac_f32_e32 v104, 0x3f317217, v85
	v_cmp_lt_f32_e64 s[46:47], |v85|, s62
	v_add_f32_e32 v109, 1.0, v109
	v_rcp_f32_e32 v111, v109
	v_cndmask_b32_e64 v85, v85, v104, s[46:47]
	v_cndmask_b32_e32 v104, 0, v225, vcc
	v_sub_f32_e32 v85, v85, v104
	v_mul_f32_e32 v104, 0xbfb8aa3b, v94
	v_exp_f32_e32 v104, v104
	v_mul_f32_e32 v105, 0x3fb8aa3b, v95
	v_mul_f32_e32 v109, 0x3fb8aa3b, v91
	v_exp_f32_e32 v105, v105
	v_add_f32_e32 v104, 1.0, v104
	v_rcp_f32_e32 v108, v104
	v_mul_f32_e32 v104, 0x3fb8aa3b, v94
	v_exp_f32_e32 v104, v104
	v_exp_f32_e32 v109, v109
	v_fma_f32 v86, v108, v106, v86
	v_max_f32_e32 v86, 0xda24260, v86
	v_cmp_gt_f32_e32 vcc, s93, v86
	v_add_f32_e32 v104, 1.0, v104
	v_add_f32_e32 v105, 1.0, v105
	v_cndmask_b32_e64 v108, 0, 32, vcc
	v_ldexp_f32 v86, v86, v108
	v_log_f32_e32 v86, v86
	v_add_f32_e32 v109, 1.0, v109
	v_rcp_f32_e32 v104, v104
	v_rcp_f32_e32 v105, v105
	v_mul_f32_e32 v108, 0x3f317217, v86
	v_fma_f32 v108, v86, s95, -v108
	v_fmac_f32_e32 v108, 0x3377d1cf, v86
	v_fmac_f32_e32 v108, 0x3f317217, v86
	v_cmp_lt_f32_e64 s[46:47], |v86|, s62
	v_rcp_f32_e32 v109, v109
	v_pk_mul_f32 v[102:103], v[100:101], v[102:103]
	v_cndmask_b32_e64 v86, v86, v108, s[46:47]
	v_cndmask_b32_e32 v108, 0, v225, vcc
	v_cmp_gt_f32_e32 vcc, s93, v87
	v_sub_f32_e32 v86, v86, v108
	v_pk_mul_f32 v[100:101], v[104:105], v[106:107]
	v_cndmask_b32_e64 v108, 0, 32, vcc
	v_ldexp_f32 v87, v87, v108
	v_log_f32_e32 v87, v87
	s_nop 0
	v_mul_f32_e32 v108, 0x3f317217, v87
	v_fma_f32 v108, v87, s95, -v108
	v_fmac_f32_e32 v108, 0x3377d1cf, v87
	v_fmac_f32_e32 v108, 0x3f317217, v87
	v_cmp_lt_f32_e64 s[46:47], |v87|, s62
	s_nop 1
	v_cndmask_b32_e64 v87, v87, v108, s[46:47]
	v_cndmask_b32_e32 v108, 0, v225, vcc
	v_sub_f32_e32 v87, v87, v108
	v_mul_f32_e32 v108, 0xbfb8aa3b, v90
	v_exp_f32_e32 v108, v108
	s_nop 0
	v_add_f32_e32 v108, 1.0, v108
	v_rcp_f32_e32 v110, v108
	v_mul_f32_e32 v108, 0x3fb8aa3b, v90
	v_exp_f32_e32 v108, v108
	v_fma_f32 v80, v110, v114, v80
	v_max_f32_e32 v80, 0xda24260, v80
	v_cmp_gt_f32_e32 vcc, s93, v80
	v_add_f32_e32 v108, 1.0, v108
	v_rcp_f32_e32 v108, v108
	v_cndmask_b32_e64 v110, 0, 32, vcc
	v_ldexp_f32 v80, v80, v110
	v_log_f32_e32 v80, v80
	s_nop 0
	v_mul_f32_e32 v110, 0x3f317217, v80
	v_fma_f32 v110, v80, s95, -v110
	v_fmac_f32_e32 v110, 0x3377d1cf, v80
	v_fmac_f32_e32 v110, 0x3f317217, v80
	v_cmp_lt_f32_e64 s[46:47], |v80|, s62
	s_nop 1
	v_cndmask_b32_e64 v80, v80, v110, s[46:47]
	v_cndmask_b32_e32 v110, 0, v225, vcc
	v_sub_f32_e32 v110, v80, v110
	v_fma_f32 v80, v111, v115, v81
	v_max_f32_e32 v80, 0xda24260, v80
	v_cmp_gt_f32_e32 vcc, s93, v80
	s_nop 1
	v_cndmask_b32_e64 v81, 0, 32, vcc
	v_ldexp_f32 v80, v80, v81
	v_log_f32_e32 v80, v80
	s_nop 0
	v_mul_f32_e32 v81, 0x3f317217, v80
	v_fma_f32 v81, v80, s95, -v81
	v_fmac_f32_e32 v81, 0x3377d1cf, v80
	v_fmac_f32_e32 v81, 0x3f317217, v80
	v_cmp_lt_f32_e64 s[46:47], |v80|, s62
	s_nop 1
	v_cndmask_b32_e64 v80, v80, v81, s[46:47]
	v_cndmask_b32_e32 v81, 0, v225, vcc
	v_sub_f32_e32 v111, v80, v81
	v_mul_f32_e32 v80, 0xbfb8aa3b, v98
	v_exp_f32_e32 v80, v80
	v_mul_f32_e32 v81, 0xbfb8aa3b, v99
	v_exp_f32_e32 v81, v81
	v_add_f32_e32 v80, 1.0, v80
	v_rcp_f32_e32 v112, v80
	v_add_f32_e32 v81, 1.0, v81
	v_rcp_f32_e32 v113, v81
	v_mul_f32_e32 v80, 0x3fb8aa3b, v98
	v_fma_f32 v82, v112, v116, v82
	v_max_f32_e32 v82, 0xda24260, v82
	v_cmp_gt_f32_e32 vcc, s93, v82
	v_fmac_f32_e32 v83, v113, v117
	v_mul_f32_e32 v81, 0x3fb8aa3b, v99
	v_cndmask_b32_e64 v112, 0, 32, vcc
	v_ldexp_f32 v82, v82, v112
	v_log_f32_e32 v82, v82
	v_exp_f32_e32 v80, v80
	v_exp_f32_e32 v81, v81
	v_mul_f32_e32 v112, 0x3f317217, v82
	v_fma_f32 v112, v82, s95, -v112
	v_fmac_f32_e32 v112, 0x3377d1cf, v82
	v_fmac_f32_e32 v112, 0x3f317217, v82
	v_cmp_lt_f32_e64 s[46:47], |v82|, s62
	v_add_f32_e32 v80, 1.0, v80
	v_add_f32_e32 v81, 1.0, v81
	v_cndmask_b32_e64 v82, v82, v112, s[46:47]
	v_cndmask_b32_e32 v112, 0, v225, vcc
	v_sub_f32_e32 v112, v82, v112
	v_max_f32_e32 v82, 0xda24260, v83
	v_cmp_gt_f32_e32 vcc, s93, v82
	v_rcp_f32_e32 v80, v80
	v_rcp_f32_e32 v81, v81
	v_cndmask_b32_e64 v83, 0, 32, vcc
	v_ldexp_f32 v82, v82, v83
	v_log_f32_e32 v82, v82
	v_pk_mul_f32 v[80:81], v[80:81], v[116:117]
	v_mul_f32_e32 v83, 0x3f317217, v82
	v_fma_f32 v83, v82, s95, -v83
	v_fmac_f32_e32 v83, 0x3377d1cf, v82
	v_fmac_f32_e32 v83, 0x3f317217, v82
	v_cmp_lt_f32_e64 s[46:47], |v82|, s62
	s_nop 1
	v_cndmask_b32_e64 v82, v82, v83, s[46:47]
	v_cndmask_b32_e32 v83, 0, v225, vcc
	v_sub_f32_e32 v113, v82, v83
	v_pk_mul_f32 v[82:83], v[108:109], v[114:115]
	global_store_dwordx4 v[96:97], v[84:87], off
	global_store_dwordx4 v[96:97], v[110:113], off offset:16

.LBB0_432:
	s_andn2_b64 vcc, exec, s[36:37]
	s_cbranch_vccnz .LBB0_434
	v_mul_f32_e32 v80, 0xbfb8aa3b, v94
	v_exp_f32_e32 v80, v80
	v_mul_f32_e32 v105, 0xbfb8aa3b, v97
	v_exp_f32_e32 v105, v105
	v_mul_f32_e32 v109, 0xbfb8aa3b, v93
	v_add_f32_e32 v80, 1.0, v80
	v_rcp_f32_e32 v91, v80
	v_mul_f32_e32 v80, 0x3fb8aa3b, v94
	v_exp_f32_e32 v80, v80
	v_add_f32_e32 v105, 1.0, v105
	v_rcp_f32_e32 v108, v105
	v_exp_f32_e32 v109, v109
	v_add_f32_e32 v80, 1.0, v80
	v_rcp_f32_e32 v100, v80
	v_mul_f32_e32 v80, 0xbfb8aa3b, v95
	v_exp_f32_e32 v80, v80
	v_add_f32_e32 v109, 1.0, v109
	v_rcp_f32_e32 v111, v109
	v_mul_f32_e32 v105, 0x3fb8aa3b, v97
	v_add_f32_e32 v80, 1.0, v80
	v_rcp_f32_e32 v104, v80
	v_mul_f32_e32 v80, 0x3fb8aa3b, v95
	v_exp_f32_e32 v80, v80
	v_mul_f32_e32 v109, 0x3fb8aa3b, v93
	v_exp_f32_e32 v105, v105
	v_exp_f32_e32 v109, v109
	v_add_f32_e32 v80, 1.0, v80
	v_rcp_f32_e32 v101, v80
	v_bfe_u32 v84, v184, 6, 2
	v_bfe_u32 v85, v184, 4, 2
	v_lshlrev_b32_e32 v84, 7, v84
	v_lshl_add_u32 v84, v85, 5, v84
	v_add_u32_e32 v84, 0x21800, v84
	ds_read_b128 v[80:83], v84 offset:16
	ds_read_b128 v[84:87], v84
	v_add_f32_e32 v105, 1.0, v105
	v_add_f32_e32 v109, 1.0, v109
	v_rcp_f32_e32 v105, v105
	v_rcp_f32_e32 v109, v109
	s_waitcnt lgkmcnt(1)
	v_pk_add_f32 v[114:115], v[80:81], 1.0 op_sel_hi:[1,0] neg_lo:[1,0] neg_hi:[1,0]
	s_waitcnt lgkmcnt(0)
	v_pk_add_f32 v[102:103], v[84:85], 1.0 op_sel_hi:[1,0] neg_lo:[1,0] neg_hi:[1,0]
	v_pk_add_f32 v[106:107], v[86:87], 1.0 op_sel_hi:[1,0] neg_lo:[1,0] neg_hi:[1,0]
	v_fma_f32 v84, v91, v102, v84
	v_max_f32_e32 v84, 0xda24260, v84
	v_cmp_gt_f32_e32 vcc, s93, v84
	v_fma_f32 v85, v104, v103, v85
	v_max_f32_e32 v85, 0xda24260, v85
	v_cndmask_b32_e64 v91, 0, 32, vcc
	v_ldexp_f32 v84, v84, v91
	v_log_f32_e32 v84, v84
	v_fmac_f32_e32 v87, v108, v107
	v_max_f32_e32 v87, 0xda24260, v87
	v_pk_add_f32 v[116:117], v[82:83], 1.0 op_sel_hi:[1,0] neg_lo:[1,0] neg_hi:[1,0]
	v_mul_f32_e32 v91, 0x3f317217, v84
	v_fma_f32 v91, v84, s95, -v91
	v_fmac_f32_e32 v91, 0x3377d1cf, v84
	v_fmac_f32_e32 v91, 0x3f317217, v84
	v_cmp_lt_f32_e64 s[46:47], |v84|, s62
	v_mul_f32_e32 v104, 0x3fb8aa3b, v96
	v_mul_f32_e32 v108, 0x3fb8aa3b, v92
	v_cndmask_b32_e64 v84, v84, v91, s[46:47]
	v_cndmask_b32_e32 v91, 0, v225, vcc
	v_cmp_gt_f32_e32 vcc, s93, v85
	v_sub_f32_e32 v84, v84, v91
	v_exp_f32_e32 v104, v104
	v_cndmask_b32_e64 v91, 0, 32, vcc
	v_ldexp_f32 v85, v85, v91
	v_log_f32_e32 v85, v85
	v_exp_f32_e32 v108, v108
	v_add_f32_e32 v104, 1.0, v104
	v_rcp_f32_e32 v104, v104
	v_mul_f32_e32 v91, 0x3f317217, v85
	v_fma_f32 v91, v85, s95, -v91
	v_fmac_f32_e32 v91, 0x3377d1cf, v85
	v_fmac_f32_e32 v91, 0x3f317217, v85
	v_cmp_lt_f32_e64 s[46:47], |v85|, s62
	v_add_f32_e32 v108, 1.0, v108
	v_rcp_f32_e32 v108, v108
	v_cndmask_b32_e64 v85, v85, v91, s[46:47]
	v_cndmask_b32_e32 v91, 0, v225, vcc
	v_sub_f32_e32 v85, v85, v91
	v_mul_f32_e32 v91, 0xbfb8aa3b, v96
	v_exp_f32_e32 v91, v91
	v_pk_mul_f32 v[102:103], v[100:101], v[102:103]
	v_pk_mul_f32 v[100:101], v[104:105], v[106:107]
	v_lshl_add_u64 v[104:105], v[146:147], 0, v[88:89]
	v_add_f32_e32 v91, 1.0, v91
	v_rcp_f32_e32 v91, v91
	s_nop 0
	v_fma_f32 v86, v91, v106, v86
	v_max_f32_e32 v86, 0xda24260, v86
	v_cmp_gt_f32_e32 vcc, s93, v86
	s_nop 1
	v_cndmask_b32_e64 v91, 0, 32, vcc
	v_ldexp_f32 v86, v86, v91
	v_log_f32_e32 v86, v86
	s_nop 0
	v_mul_f32_e32 v91, 0x3f317217, v86
	v_fma_f32 v91, v86, s95, -v91
	v_fmac_f32_e32 v91, 0x3377d1cf, v86
	v_fmac_f32_e32 v91, 0x3f317217, v86
	v_cmp_lt_f32_e64 s[46:47], |v86|, s62
	s_nop 1
	v_cndmask_b32_e64 v86, v86, v91, s[46:47]
	v_cndmask_b32_e32 v91, 0, v225, vcc
	v_cmp_gt_f32_e32 vcc, s93, v87
	v_sub_f32_e32 v86, v86, v91
	s_nop 0
	v_cndmask_b32_e64 v91, 0, 32, vcc
	v_ldexp_f32 v87, v87, v91
	v_log_f32_e32 v87, v87
	s_nop 0
	v_mul_f32_e32 v91, 0x3f317217, v87
	v_fma_f32 v91, v87, s95, -v91
	v_fmac_f32_e32 v91, 0x3377d1cf, v87
	v_fmac_f32_e32 v91, 0x3f317217, v87
	v_cmp_lt_f32_e64 s[46:47], |v87|, s62
	s_nop 1
	v_cndmask_b32_e64 v87, v87, v91, s[46:47]
	v_cndmask_b32_e32 v91, 0, v225, vcc
	v_sub_f32_e32 v87, v87, v91
	v_mul_f32_e32 v91, 0xbfb8aa3b, v92
	v_exp_f32_e32 v91, v91
	s_nop 0
	v_add_f32_e32 v91, 1.0, v91
	v_rcp_f32_e32 v91, v91
	s_nop 0
	v_fma_f32 v80, v91, v114, v80
	v_max_f32_e32 v80, 0xda24260, v80
	v_cmp_gt_f32_e32 vcc, s93, v80
	s_nop 1
	v_cndmask_b32_e64 v91, 0, 32, vcc
	v_ldexp_f32 v80, v80, v91
	v_log_f32_e32 v80, v80
	s_nop 0
	v_mul_f32_e32 v91, 0x3f317217, v80
	v_fma_f32 v91, v80, s95, -v91
	v_fmac_f32_e32 v91, 0x3377d1cf, v80
	v_fmac_f32_e32 v91, 0x3f317217, v80
	v_cmp_lt_f32_e64 s[46:47], |v80|, s62
	s_nop 1
	v_cndmask_b32_e64 v80, v80, v91, s[46:47]
	v_cndmask_b32_e32 v91, 0, v225, vcc
	v_sub_f32_e32 v110, v80, v91
	v_fma_f32 v80, v111, v115, v81
	v_max_f32_e32 v80, 0xda24260, v80
	v_cmp_gt_f32_e32 vcc, s93, v80
	s_nop 1
	v_cndmask_b32_e64 v81, 0, 32, vcc
	v_ldexp_f32 v80, v80, v81
	v_log_f32_e32 v80, v80
	s_nop 0
	v_mul_f32_e32 v81, 0x3f317217, v80
	v_fma_f32 v81, v80, s95, -v81
	v_fmac_f32_e32 v81, 0x3377d1cf, v80
	v_fmac_f32_e32 v81, 0x3f317217, v80
	v_cmp_lt_f32_e64 s[46:47], |v80|, s62
	s_nop 1
	v_cndmask_b32_e64 v80, v80, v81, s[46:47]
	v_cndmask_b32_e32 v81, 0, v225, vcc
	v_sub_f32_e32 v111, v80, v81
	v_mul_f32_e32 v80, 0xbfb8aa3b, v98
	v_exp_f32_e32 v80, v80
	v_mul_f32_e32 v81, 0xbfb8aa3b, v99
	v_exp_f32_e32 v81, v81
	v_add_f32_e32 v80, 1.0, v80
	v_rcp_f32_e32 v91, v80
	v_add_f32_e32 v81, 1.0, v81
	v_rcp_f32_e32 v113, v81
	v_mul_f32_e32 v80, 0x3fb8aa3b, v98
	v_fma_f32 v82, v91, v116, v82
	v_max_f32_e32 v82, 0xda24260, v82
	v_cmp_gt_f32_e32 vcc, s93, v82
	v_fmac_f32_e32 v83, v113, v117
	v_mul_f32_e32 v81, 0x3fb8aa3b, v99
	v_cndmask_b32_e64 v91, 0, 32, vcc
	v_ldexp_f32 v82, v82, v91
	v_log_f32_e32 v82, v82
	v_exp_f32_e32 v80, v80
	v_exp_f32_e32 v81, v81
	v_mul_f32_e32 v91, 0x3f317217, v82
	v_fma_f32 v91, v82, s95, -v91
	v_fmac_f32_e32 v91, 0x3377d1cf, v82
	v_fmac_f32_e32 v91, 0x3f317217, v82
	v_cmp_lt_f32_e64 s[46:47], |v82|, s62
	v_add_f32_e32 v80, 1.0, v80
	v_add_f32_e32 v81, 1.0, v81
	v_cndmask_b32_e64 v82, v82, v91, s[46:47]
	v_cndmask_b32_e32 v91, 0, v225, vcc
	v_sub_f32_e32 v112, v82, v91
	v_max_f32_e32 v82, 0xda24260, v83
	v_cmp_gt_f32_e32 vcc, s93, v82
	v_rcp_f32_e32 v80, v80
	v_rcp_f32_e32 v81, v81
	v_cndmask_b32_e64 v83, 0, 32, vcc
	v_ldexp_f32 v82, v82, v83
	v_log_f32_e32 v82, v82
	v_pk_mul_f32 v[80:81], v[80:81], v[116:117]
	v_mul_f32_e32 v83, 0x3f317217, v82
	v_fma_f32 v83, v82, s95, -v83
	v_fmac_f32_e32 v83, 0x3377d1cf, v82
	v_fmac_f32_e32 v83, 0x3f317217, v82
	v_cmp_lt_f32_e64 s[46:47], |v82|, s62
	s_nop 1
	v_cndmask_b32_e64 v82, v82, v83, s[46:47]
	v_cndmask_b32_e32 v83, 0, v225, vcc
	v_sub_f32_e32 v113, v82, v83
	v_pk_mul_f32 v[82:83], v[108:109], v[114:115]
	global_store_dwordx4 v[104:105], v[84:87], off
	global_store_dwordx4 v[104:105], v[110:113], off offset:16

.LBB0_444:
	s_andn2_b64 vcc, exec, s[36:37]
	s_cbranch_vccnz .LBB0_446
	v_bfe_u32 v76, v184, 6, 2
	v_bfe_u32 v77, v184, 4, 2
	v_lshlrev_b32_e32 v76, 7, v76
	v_lshl_add_u32 v76, v77, 5, v76
	v_add_u32_e32 v76, 0x21800, v76
	ds_read_b128 v[72:75], v76 offset:528
	ds_read_b128 v[76:79], v76 offset:512
	v_mul_f32_e32 v92, 0xbfb8aa3b, v84
	v_exp_f32_e32 v92, v92
	v_mul_f32_e32 v93, 0xbfb8aa3b, v85
	v_exp_f32_e32 v93, v93
	v_lshl_add_u64 v[88:89], v[150:151], 0, v[88:89]
	v_add_f32_e32 v92, 1.0, v92
	v_rcp_f32_e32 v96, v92
	v_add_f32_e32 v93, 1.0, v93
	v_rcp_f32_e32 v97, v93
	v_mul_f32_e32 v92, 0x3fb8aa3b, v84
	v_mul_f32_e32 v93, 0x3fb8aa3b, v85
	v_exp_f32_e32 v92, v92
	v_exp_f32_e32 v93, v93
	v_add_f32_e32 v92, 1.0, v92
	v_add_f32_e32 v93, 1.0, v93
	v_rcp_f32_e32 v92, v92
	v_rcp_f32_e32 v93, v93
	s_waitcnt lgkmcnt(1)
	v_pk_add_f32 v[106:107], v[72:73], 1.0 op_sel_hi:[1,0] neg_lo:[1,0] neg_hi:[1,0]
	s_waitcnt lgkmcnt(0)
	v_pk_add_f32 v[94:95], v[76:77], 1.0 op_sel_hi:[1,0] neg_lo:[1,0] neg_hi:[1,0]
	v_pk_add_f32 v[98:99], v[78:79], 1.0 op_sel_hi:[1,0] neg_lo:[1,0] neg_hi:[1,0]
	v_fma_f32 v76, v96, v94, v76
	v_max_f32_e32 v76, 0xda24260, v76
	v_cmp_gt_f32_e32 vcc, s93, v76
	v_fma_f32 v77, v97, v95, v77
	v_max_f32_e32 v77, 0xda24260, v77
	v_cndmask_b32_e64 v96, 0, 32, vcc
	v_ldexp_f32 v76, v76, v96
	v_log_f32_e32 v76, v76
	v_mul_f32_e32 v97, 0xbfb8aa3b, v87
	v_exp_f32_e32 v97, v97
	v_pk_add_f32 v[108:109], v[74:75], 1.0 op_sel_hi:[1,0] neg_lo:[1,0] neg_hi:[1,0]
	v_mul_f32_e32 v96, 0x3f317217, v76
	v_fma_f32 v96, v76, s95, -v96
	v_fmac_f32_e32 v96, 0x3377d1cf, v76
	v_fmac_f32_e32 v96, 0x3f317217, v76
	v_cmp_lt_f32_e64 s[46:47], |v76|, s62
	v_add_f32_e32 v97, 1.0, v97
	v_rcp_f32_e32 v101, v97
	v_cndmask_b32_e64 v76, v76, v96, s[46:47]
	v_cndmask_b32_e32 v96, 0, v225, vcc
	v_cmp_gt_f32_e32 vcc, s93, v77
	v_sub_f32_e32 v76, v76, v96
	v_fmac_f32_e32 v79, v101, v99
	v_cndmask_b32_e64 v96, 0, 32, vcc
	v_ldexp_f32 v77, v77, v96
	v_log_f32_e32 v77, v77
	v_max_f32_e32 v79, 0xda24260, v79
	v_mul_f32_e32 v101, 0xbfb8aa3b, v83
	v_exp_f32_e32 v101, v101
	v_mul_f32_e32 v96, 0x3f317217, v77
	v_fma_f32 v96, v77, s95, -v96
	v_fmac_f32_e32 v96, 0x3377d1cf, v77
	v_fmac_f32_e32 v96, 0x3f317217, v77
	v_cmp_lt_f32_e64 s[46:47], |v77|, s62
	v_add_f32_e32 v101, 1.0, v101
	v_rcp_f32_e32 v103, v101
	v_cndmask_b32_e64 v77, v77, v96, s[46:47]
	v_cndmask_b32_e32 v96, 0, v225, vcc
	v_sub_f32_e32 v77, v77, v96
	v_mul_f32_e32 v96, 0xbfb8aa3b, v86
	v_exp_f32_e32 v96, v96
	v_mul_f32_e32 v97, 0x3fb8aa3b, v87
	v_mul_f32_e32 v101, 0x3fb8aa3b, v83
	v_exp_f32_e32 v97, v97
	v_add_f32_e32 v96, 1.0, v96
	v_rcp_f32_e32 v100, v96
	v_mul_f32_e32 v96, 0x3fb8aa3b, v86
	v_exp_f32_e32 v96, v96
	v_exp_f32_e32 v101, v101
	v_fma_f32 v78, v100, v98, v78
	v_max_f32_e32 v78, 0xda24260, v78
	v_cmp_gt_f32_e32 vcc, s93, v78
	v_add_f32_e32 v96, 1.0, v96
	v_add_f32_e32 v97, 1.0, v97
	v_cndmask_b32_e64 v100, 0, 32, vcc
	v_ldexp_f32 v78, v78, v100
	v_log_f32_e32 v78, v78
	v_add_f32_e32 v101, 1.0, v101
	v_rcp_f32_e32 v96, v96
	v_rcp_f32_e32 v97, v97
	v_mul_f32_e32 v100, 0x3f317217, v78
	v_fma_f32 v100, v78, s95, -v100
	v_fmac_f32_e32 v100, 0x3377d1cf, v78
	v_fmac_f32_e32 v100, 0x3f317217, v78
	v_cmp_lt_f32_e64 s[46:47], |v78|, s62
	v_rcp_f32_e32 v101, v101
	v_pk_mul_f32 v[94:95], v[92:93], v[94:95]
	v_cndmask_b32_e64 v78, v78, v100, s[46:47]
	v_cndmask_b32_e32 v100, 0, v225, vcc
	v_cmp_gt_f32_e32 vcc, s93, v79
	v_sub_f32_e32 v78, v78, v100
	v_pk_mul_f32 v[92:93], v[96:97], v[98:99]
	v_cndmask_b32_e64 v100, 0, 32, vcc
	v_ldexp_f32 v79, v79, v100
	v_log_f32_e32 v79, v79
	s_nop 0
	v_mul_f32_e32 v100, 0x3f317217, v79
	v_fma_f32 v100, v79, s95, -v100
	v_fmac_f32_e32 v100, 0x3377d1cf, v79
	v_fmac_f32_e32 v100, 0x3f317217, v79
	v_cmp_lt_f32_e64 s[46:47], |v79|, s62
	s_nop 1
	v_cndmask_b32_e64 v79, v79, v100, s[46:47]
	v_cndmask_b32_e32 v100, 0, v225, vcc
	v_sub_f32_e32 v79, v79, v100
	v_mul_f32_e32 v100, 0xbfb8aa3b, v82
	v_exp_f32_e32 v100, v100
	s_nop 0
	v_add_f32_e32 v100, 1.0, v100
	v_rcp_f32_e32 v102, v100
	v_mul_f32_e32 v100, 0x3fb8aa3b, v82
	v_exp_f32_e32 v100, v100
	v_fma_f32 v72, v102, v106, v72
	v_max_f32_e32 v72, 0xda24260, v72
	v_cmp_gt_f32_e32 vcc, s93, v72
	v_add_f32_e32 v100, 1.0, v100
	v_rcp_f32_e32 v100, v100
	v_cndmask_b32_e64 v102, 0, 32, vcc
	v_ldexp_f32 v72, v72, v102
	v_log_f32_e32 v72, v72
	s_nop 0
	v_mul_f32_e32 v102, 0x3f317217, v72
	v_fma_f32 v102, v72, s95, -v102
	v_fmac_f32_e32 v102, 0x3377d1cf, v72
	v_fmac_f32_e32 v102, 0x3f317217, v72
	v_cmp_lt_f32_e64 s[46:47], |v72|, s62
	s_nop 1
	v_cndmask_b32_e64 v72, v72, v102, s[46:47]
	v_cndmask_b32_e32 v102, 0, v225, vcc
	v_sub_f32_e32 v102, v72, v102
	v_fma_f32 v72, v103, v107, v73
	v_max_f32_e32 v72, 0xda24260, v72
	v_cmp_gt_f32_e32 vcc, s93, v72
	s_nop 1
	v_cndmask_b32_e64 v73, 0, 32, vcc
	v_ldexp_f32 v72, v72, v73
	v_log_f32_e32 v72, v72
	s_nop 0
	v_mul_f32_e32 v73, 0x3f317217, v72
	v_fma_f32 v73, v72, s95, -v73
	v_fmac_f32_e32 v73, 0x3377d1cf, v72
	v_fmac_f32_e32 v73, 0x3f317217, v72
	v_cmp_lt_f32_e64 s[46:47], |v72|, s62
	s_nop 1
	v_cndmask_b32_e64 v72, v72, v73, s[46:47]
	v_cndmask_b32_e32 v73, 0, v225, vcc
	v_sub_f32_e32 v103, v72, v73
	v_mul_f32_e32 v72, 0xbfb8aa3b, v90
	v_exp_f32_e32 v72, v72
	v_mul_f32_e32 v73, 0xbfb8aa3b, v91
	v_exp_f32_e32 v73, v73
	v_add_f32_e32 v72, 1.0, v72
	v_rcp_f32_e32 v104, v72
	v_add_f32_e32 v73, 1.0, v73
	v_rcp_f32_e32 v105, v73
	v_mul_f32_e32 v72, 0x3fb8aa3b, v90
	v_fma_f32 v74, v104, v108, v74
	v_max_f32_e32 v74, 0xda24260, v74
	v_cmp_gt_f32_e32 vcc, s93, v74
	v_fmac_f32_e32 v75, v105, v109
	v_mul_f32_e32 v73, 0x3fb8aa3b, v91
	v_cndmask_b32_e64 v104, 0, 32, vcc
	v_ldexp_f32 v74, v74, v104
	v_log_f32_e32 v74, v74
	v_exp_f32_e32 v72, v72
	v_exp_f32_e32 v73, v73
	v_mul_f32_e32 v104, 0x3f317217, v74
	v_fma_f32 v104, v74, s95, -v104
	v_fmac_f32_e32 v104, 0x3377d1cf, v74
	v_fmac_f32_e32 v104, 0x3f317217, v74
	v_cmp_lt_f32_e64 s[46:47], |v74|, s62
	v_add_f32_e32 v72, 1.0, v72
	v_add_f32_e32 v73, 1.0, v73
	v_cndmask_b32_e64 v74, v74, v104, s[46:47]
	v_cndmask_b32_e32 v104, 0, v225, vcc
	v_sub_f32_e32 v104, v74, v104
	v_max_f32_e32 v74, 0xda24260, v75
	v_cmp_gt_f32_e32 vcc, s93, v74
	v_rcp_f32_e32 v72, v72
	v_rcp_f32_e32 v73, v73
	v_cndmask_b32_e64 v75, 0, 32, vcc
	v_ldexp_f32 v74, v74, v75
	v_log_f32_e32 v74, v74
	v_pk_mul_f32 v[72:73], v[72:73], v[108:109]
	v_mul_f32_e32 v75, 0x3f317217, v74
	v_fma_f32 v75, v74, s95, -v75
	v_fmac_f32_e32 v75, 0x3377d1cf, v74
	v_fmac_f32_e32 v75, 0x3f317217, v74
	v_cmp_lt_f32_e64 s[46:47], |v74|, s62
	s_nop 1
	v_cndmask_b32_e64 v74, v74, v75, s[46:47]
	v_cndmask_b32_e32 v75, 0, v225, vcc
	v_sub_f32_e32 v105, v74, v75
	v_pk_mul_f32 v[74:75], v[100:101], v[106:107]
	global_store_dwordx4 v[88:89], v[76:79], off
	global_store_dwordx4 v[88:89], v[102:105], off offset:16

.LBB0_456:
	s_andn2_b64 vcc, exec, s[36:37]
	s_cbranch_vccnz .LBB0_458
	v_mul_f32_e32 v72, 0xbfb8aa3b, v86
	v_exp_f32_e32 v72, v72
	v_mul_f32_e32 v97, 0xbfb8aa3b, v89
	v_exp_f32_e32 v97, v97
	v_mul_f32_e32 v101, 0xbfb8aa3b, v85
	v_add_f32_e32 v72, 1.0, v72
	v_rcp_f32_e32 v83, v72
	v_mul_f32_e32 v72, 0x3fb8aa3b, v86
	v_exp_f32_e32 v72, v72
	v_add_f32_e32 v97, 1.0, v97
	v_rcp_f32_e32 v100, v97
	v_exp_f32_e32 v101, v101
	v_add_f32_e32 v72, 1.0, v72
	v_rcp_f32_e32 v92, v72
	v_mul_f32_e32 v72, 0xbfb8aa3b, v87
	v_exp_f32_e32 v72, v72
	v_add_f32_e32 v101, 1.0, v101
	v_rcp_f32_e32 v103, v101
	v_mul_f32_e32 v97, 0x3fb8aa3b, v89
	v_add_f32_e32 v72, 1.0, v72
	v_rcp_f32_e32 v96, v72
	v_mul_f32_e32 v72, 0x3fb8aa3b, v87
	v_exp_f32_e32 v72, v72
	v_mul_f32_e32 v101, 0x3fb8aa3b, v85
	v_exp_f32_e32 v97, v97
	v_exp_f32_e32 v101, v101
	v_add_f32_e32 v72, 1.0, v72
	v_rcp_f32_e32 v93, v72
	v_bfe_u32 v76, v184, 6, 2
	v_bfe_u32 v77, v184, 4, 2
	v_lshlrev_b32_e32 v76, 7, v76
	v_lshl_add_u32 v76, v77, 5, v76
	v_add_u32_e32 v76, 0x21800, v76
	ds_read_b128 v[72:75], v76 offset:16
	ds_read_b128 v[76:79], v76
	v_add_f32_e32 v97, 1.0, v97
	v_add_f32_e32 v101, 1.0, v101
	v_rcp_f32_e32 v97, v97
	v_rcp_f32_e32 v101, v101
	s_waitcnt lgkmcnt(1)
	v_pk_add_f32 v[106:107], v[72:73], 1.0 op_sel_hi:[1,0] neg_lo:[1,0] neg_hi:[1,0]
	s_waitcnt lgkmcnt(0)
	v_pk_add_f32 v[94:95], v[76:77], 1.0 op_sel_hi:[1,0] neg_lo:[1,0] neg_hi:[1,0]
	v_pk_add_f32 v[98:99], v[78:79], 1.0 op_sel_hi:[1,0] neg_lo:[1,0] neg_hi:[1,0]
	v_fma_f32 v76, v83, v94, v76
	v_max_f32_e32 v76, 0xda24260, v76
	v_cmp_gt_f32_e32 vcc, s93, v76
	v_fma_f32 v77, v96, v95, v77
	v_max_f32_e32 v77, 0xda24260, v77
	v_cndmask_b32_e64 v83, 0, 32, vcc
	v_ldexp_f32 v76, v76, v83
	v_log_f32_e32 v76, v76
	v_fmac_f32_e32 v79, v100, v99
	v_max_f32_e32 v79, 0xda24260, v79
	v_pk_add_f32 v[108:109], v[74:75], 1.0 op_sel_hi:[1,0] neg_lo:[1,0] neg_hi:[1,0]
	v_mul_f32_e32 v83, 0x3f317217, v76
	v_fma_f32 v83, v76, s95, -v83
	v_fmac_f32_e32 v83, 0x3377d1cf, v76
	v_fmac_f32_e32 v83, 0x3f317217, v76
	v_cmp_lt_f32_e64 s[46:47], |v76|, s62
	v_mul_f32_e32 v96, 0x3fb8aa3b, v88
	v_mul_f32_e32 v100, 0x3fb8aa3b, v84
	v_cndmask_b32_e64 v76, v76, v83, s[46:47]
	v_cndmask_b32_e32 v83, 0, v225, vcc
	v_cmp_gt_f32_e32 vcc, s93, v77
	v_sub_f32_e32 v76, v76, v83
	v_exp_f32_e32 v96, v96
	v_cndmask_b32_e64 v83, 0, 32, vcc
	v_ldexp_f32 v77, v77, v83
	v_log_f32_e32 v77, v77
	v_exp_f32_e32 v100, v100
	v_add_f32_e32 v96, 1.0, v96
	v_rcp_f32_e32 v96, v96
	v_mul_f32_e32 v83, 0x3f317217, v77
	v_fma_f32 v83, v77, s95, -v83
	v_fmac_f32_e32 v83, 0x3377d1cf, v77
	v_fmac_f32_e32 v83, 0x3f317217, v77
	v_cmp_lt_f32_e64 s[46:47], |v77|, s62
	v_add_f32_e32 v100, 1.0, v100
	v_rcp_f32_e32 v100, v100
	v_cndmask_b32_e64 v77, v77, v83, s[46:47]
	v_cndmask_b32_e32 v83, 0, v225, vcc
	v_sub_f32_e32 v77, v77, v83
	v_mul_f32_e32 v83, 0xbfb8aa3b, v88
	v_exp_f32_e32 v83, v83
	v_pk_mul_f32 v[94:95], v[92:93], v[94:95]
	v_pk_mul_f32 v[92:93], v[96:97], v[98:99]
	v_lshl_add_u64 v[96:97], v[146:147], 0, v[80:81]
	v_add_f32_e32 v83, 1.0, v83
	v_rcp_f32_e32 v83, v83
	s_nop 0
	v_fma_f32 v78, v83, v98, v78
	v_max_f32_e32 v78, 0xda24260, v78
	v_cmp_gt_f32_e32 vcc, s93, v78
	s_nop 1
	v_cndmask_b32_e64 v83, 0, 32, vcc
	v_ldexp_f32 v78, v78, v83
	v_log_f32_e32 v78, v78
	s_nop 0
	v_mul_f32_e32 v83, 0x3f317217, v78
	v_fma_f32 v83, v78, s95, -v83
	v_fmac_f32_e32 v83, 0x3377d1cf, v78
	v_fmac_f32_e32 v83, 0x3f317217, v78
	v_cmp_lt_f32_e64 s[46:47], |v78|, s62
	s_nop 1
	v_cndmask_b32_e64 v78, v78, v83, s[46:47]
	v_cndmask_b32_e32 v83, 0, v225, vcc
	v_cmp_gt_f32_e32 vcc, s93, v79
	v_sub_f32_e32 v78, v78, v83
	s_nop 0
	v_cndmask_b32_e64 v83, 0, 32, vcc
	v_ldexp_f32 v79, v79, v83
	v_log_f32_e32 v79, v79
	s_nop 0
	v_mul_f32_e32 v83, 0x3f317217, v79
	v_fma_f32 v83, v79, s95, -v83
	v_fmac_f32_e32 v83, 0x3377d1cf, v79
	v_fmac_f32_e32 v83, 0x3f317217, v79
	v_cmp_lt_f32_e64 s[46:47], |v79|, s62
	s_nop 1
	v_cndmask_b32_e64 v79, v79, v83, s[46:47]
	v_cndmask_b32_e32 v83, 0, v225, vcc
	v_sub_f32_e32 v79, v79, v83
	v_mul_f32_e32 v83, 0xbfb8aa3b, v84
	v_exp_f32_e32 v83, v83
	s_nop 0
	v_add_f32_e32 v83, 1.0, v83
	v_rcp_f32_e32 v83, v83
	s_nop 0
	v_fma_f32 v72, v83, v106, v72
	v_max_f32_e32 v72, 0xda24260, v72
	v_cmp_gt_f32_e32 vcc, s93, v72
	s_nop 1
	v_cndmask_b32_e64 v83, 0, 32, vcc
	v_ldexp_f32 v72, v72, v83
	v_log_f32_e32 v72, v72
	s_nop 0
	v_mul_f32_e32 v83, 0x3f317217, v72
	v_fma_f32 v83, v72, s95, -v83
	v_fmac_f32_e32 v83, 0x3377d1cf, v72
	v_fmac_f32_e32 v83, 0x3f317217, v72
	v_cmp_lt_f32_e64 s[46:47], |v72|, s62
	s_nop 1
	v_cndmask_b32_e64 v72, v72, v83, s[46:47]
	v_cndmask_b32_e32 v83, 0, v225, vcc
	v_sub_f32_e32 v102, v72, v83
	v_fma_f32 v72, v103, v107, v73
	v_max_f32_e32 v72, 0xda24260, v72
	v_cmp_gt_f32_e32 vcc, s93, v72
	s_nop 1
	v_cndmask_b32_e64 v73, 0, 32, vcc
	v_ldexp_f32 v72, v72, v73
	v_log_f32_e32 v72, v72
	s_nop 0
	v_mul_f32_e32 v73, 0x3f317217, v72
	v_fma_f32 v73, v72, s95, -v73
	v_fmac_f32_e32 v73, 0x3377d1cf, v72
	v_fmac_f32_e32 v73, 0x3f317217, v72
	v_cmp_lt_f32_e64 s[46:47], |v72|, s62
	s_nop 1
	v_cndmask_b32_e64 v72, v72, v73, s[46:47]
	v_cndmask_b32_e32 v73, 0, v225, vcc
	v_sub_f32_e32 v103, v72, v73
	v_mul_f32_e32 v72, 0xbfb8aa3b, v90
	v_exp_f32_e32 v72, v72
	v_mul_f32_e32 v73, 0xbfb8aa3b, v91
	v_exp_f32_e32 v73, v73
	v_add_f32_e32 v72, 1.0, v72
	v_rcp_f32_e32 v83, v72
	v_add_f32_e32 v73, 1.0, v73
	v_rcp_f32_e32 v105, v73
	v_mul_f32_e32 v72, 0x3fb8aa3b, v90
	v_fma_f32 v74, v83, v108, v74
	v_max_f32_e32 v74, 0xda24260, v74
	v_cmp_gt_f32_e32 vcc, s93, v74
	v_fmac_f32_e32 v75, v105, v109
	v_mul_f32_e32 v73, 0x3fb8aa3b, v91
	v_cndmask_b32_e64 v83, 0, 32, vcc
	v_ldexp_f32 v74, v74, v83
	v_log_f32_e32 v74, v74
	v_exp_f32_e32 v72, v72
	v_exp_f32_e32 v73, v73
	v_mul_f32_e32 v83, 0x3f317217, v74
	v_fma_f32 v83, v74, s95, -v83
	v_fmac_f32_e32 v83, 0x3377d1cf, v74
	v_fmac_f32_e32 v83, 0x3f317217, v74
	v_cmp_lt_f32_e64 s[46:47], |v74|, s62
	v_add_f32_e32 v72, 1.0, v72
	v_add_f32_e32 v73, 1.0, v73
	v_cndmask_b32_e64 v74, v74, v83, s[46:47]
	v_cndmask_b32_e32 v83, 0, v225, vcc
	v_sub_f32_e32 v104, v74, v83
	v_max_f32_e32 v74, 0xda24260, v75
	v_cmp_gt_f32_e32 vcc, s93, v74
	v_rcp_f32_e32 v72, v72
	v_rcp_f32_e32 v73, v73
	v_cndmask_b32_e64 v75, 0, 32, vcc
	v_ldexp_f32 v74, v74, v75
	v_log_f32_e32 v74, v74
	v_pk_mul_f32 v[72:73], v[72:73], v[108:109]
	v_mul_f32_e32 v75, 0x3f317217, v74
	v_fma_f32 v75, v74, s95, -v75
	v_fmac_f32_e32 v75, 0x3377d1cf, v74
	v_fmac_f32_e32 v75, 0x3f317217, v74
	v_cmp_lt_f32_e64 s[46:47], |v74|, s62
	s_nop 1
	v_cndmask_b32_e64 v74, v74, v75, s[46:47]
	v_cndmask_b32_e32 v75, 0, v225, vcc
	v_sub_f32_e32 v105, v74, v75
	v_pk_mul_f32 v[74:75], v[100:101], v[106:107]
	global_store_dwordx4 v[96:97], v[76:79], off
	global_store_dwordx4 v[96:97], v[102:105], off offset:16

.LBB0_468:
	s_andn2_b64 vcc, exec, s[30:31]
	s_cbranch_vccnz .LBB0_470
	v_bfe_u32 v68, v184, 6, 2
	v_bfe_u32 v69, v184, 4, 2
	v_lshlrev_b32_e32 v68, 7, v68
	v_lshl_add_u32 v68, v69, 5, v68
	v_add_u32_e32 v68, 0x21800, v68
	ds_read_b128 v[64:67], v68 offset:528
	ds_read_b128 v[68:71], v68 offset:512
	v_mul_f32_e32 v84, 0xbfb8aa3b, v76
	v_exp_f32_e32 v84, v84
	v_mul_f32_e32 v85, 0xbfb8aa3b, v77
	v_exp_f32_e32 v85, v85
	v_lshl_add_u64 v[80:81], v[150:151], 0, v[80:81]
	v_add_f32_e32 v84, 1.0, v84
	v_rcp_f32_e32 v88, v84
	v_add_f32_e32 v85, 1.0, v85
	v_rcp_f32_e32 v89, v85
	v_mul_f32_e32 v84, 0x3fb8aa3b, v76
	v_mul_f32_e32 v85, 0x3fb8aa3b, v77
	v_exp_f32_e32 v84, v84
	v_exp_f32_e32 v85, v85
	v_add_f32_e32 v84, 1.0, v84
	v_add_f32_e32 v85, 1.0, v85
	v_rcp_f32_e32 v84, v84
	v_rcp_f32_e32 v85, v85
	s_waitcnt lgkmcnt(1)
	v_pk_add_f32 v[98:99], v[64:65], 1.0 op_sel_hi:[1,0] neg_lo:[1,0] neg_hi:[1,0]
	s_waitcnt lgkmcnt(0)
	v_pk_add_f32 v[86:87], v[68:69], 1.0 op_sel_hi:[1,0] neg_lo:[1,0] neg_hi:[1,0]
	v_pk_add_f32 v[90:91], v[70:71], 1.0 op_sel_hi:[1,0] neg_lo:[1,0] neg_hi:[1,0]
	v_fma_f32 v68, v88, v86, v68
	v_max_f32_e32 v68, 0xda24260, v68
	v_cmp_gt_f32_e32 vcc, s93, v68
	v_fma_f32 v69, v89, v87, v69
	v_max_f32_e32 v69, 0xda24260, v69
	v_cndmask_b32_e64 v88, 0, 32, vcc
	v_ldexp_f32 v68, v68, v88
	v_log_f32_e32 v68, v68
	v_mul_f32_e32 v89, 0xbfb8aa3b, v79
	v_exp_f32_e32 v89, v89
	v_pk_add_f32 v[100:101], v[66:67], 1.0 op_sel_hi:[1,0] neg_lo:[1,0] neg_hi:[1,0]
	v_mul_f32_e32 v88, 0x3f317217, v68
	v_fma_f32 v88, v68, s95, -v88
	v_fmac_f32_e32 v88, 0x3377d1cf, v68
	v_fmac_f32_e32 v88, 0x3f317217, v68
	v_cmp_lt_f32_e64 s[42:43], |v68|, s62
	v_add_f32_e32 v89, 1.0, v89
	v_rcp_f32_e32 v93, v89
	v_cndmask_b32_e64 v68, v68, v88, s[42:43]
	v_cndmask_b32_e32 v88, 0, v225, vcc
	v_cmp_gt_f32_e32 vcc, s93, v69
	v_sub_f32_e32 v68, v68, v88
	v_fmac_f32_e32 v71, v93, v91
	v_cndmask_b32_e64 v88, 0, 32, vcc
	v_ldexp_f32 v69, v69, v88
	v_log_f32_e32 v69, v69
	v_max_f32_e32 v71, 0xda24260, v71
	v_mul_f32_e32 v93, 0xbfb8aa3b, v75
	v_exp_f32_e32 v93, v93
	v_mul_f32_e32 v88, 0x3f317217, v69
	v_fma_f32 v88, v69, s95, -v88
	v_fmac_f32_e32 v88, 0x3377d1cf, v69
	v_fmac_f32_e32 v88, 0x3f317217, v69
	v_cmp_lt_f32_e64 s[42:43], |v69|, s62
	v_add_f32_e32 v93, 1.0, v93
	v_rcp_f32_e32 v95, v93
	v_cndmask_b32_e64 v69, v69, v88, s[42:43]
	v_cndmask_b32_e32 v88, 0, v225, vcc
	v_sub_f32_e32 v69, v69, v88
	v_mul_f32_e32 v88, 0xbfb8aa3b, v78
	v_exp_f32_e32 v88, v88
	v_mul_f32_e32 v89, 0x3fb8aa3b, v79
	v_mul_f32_e32 v93, 0x3fb8aa3b, v75
	v_exp_f32_e32 v89, v89
	v_add_f32_e32 v88, 1.0, v88
	v_rcp_f32_e32 v92, v88
	v_mul_f32_e32 v88, 0x3fb8aa3b, v78
	v_exp_f32_e32 v88, v88
	v_exp_f32_e32 v93, v93
	v_fma_f32 v70, v92, v90, v70
	v_max_f32_e32 v70, 0xda24260, v70
	v_cmp_gt_f32_e32 vcc, s93, v70
	v_add_f32_e32 v88, 1.0, v88
	v_add_f32_e32 v89, 1.0, v89
	v_cndmask_b32_e64 v92, 0, 32, vcc
	v_ldexp_f32 v70, v70, v92
	v_log_f32_e32 v70, v70
	v_add_f32_e32 v93, 1.0, v93
	v_rcp_f32_e32 v88, v88
	v_rcp_f32_e32 v89, v89
	v_mul_f32_e32 v92, 0x3f317217, v70
	v_fma_f32 v92, v70, s95, -v92
	v_fmac_f32_e32 v92, 0x3377d1cf, v70
	v_fmac_f32_e32 v92, 0x3f317217, v70
	v_cmp_lt_f32_e64 s[42:43], |v70|, s62
	v_rcp_f32_e32 v93, v93
	v_pk_mul_f32 v[86:87], v[84:85], v[86:87]
	v_cndmask_b32_e64 v70, v70, v92, s[42:43]
	v_cndmask_b32_e32 v92, 0, v225, vcc
	v_cmp_gt_f32_e32 vcc, s93, v71
	v_sub_f32_e32 v70, v70, v92
	v_pk_mul_f32 v[84:85], v[88:89], v[90:91]
	v_cndmask_b32_e64 v92, 0, 32, vcc
	v_ldexp_f32 v71, v71, v92
	v_log_f32_e32 v71, v71
	s_nop 0
	v_mul_f32_e32 v92, 0x3f317217, v71
	v_fma_f32 v92, v71, s95, -v92
	v_fmac_f32_e32 v92, 0x3377d1cf, v71
	v_fmac_f32_e32 v92, 0x3f317217, v71
	v_cmp_lt_f32_e64 s[42:43], |v71|, s62
	s_nop 1
	v_cndmask_b32_e64 v71, v71, v92, s[42:43]
	v_cndmask_b32_e32 v92, 0, v225, vcc
	v_sub_f32_e32 v71, v71, v92
	v_mul_f32_e32 v92, 0xbfb8aa3b, v74
	v_exp_f32_e32 v92, v92
	s_nop 0
	v_add_f32_e32 v92, 1.0, v92
	v_rcp_f32_e32 v94, v92
	v_mul_f32_e32 v92, 0x3fb8aa3b, v74
	v_exp_f32_e32 v92, v92
	v_fma_f32 v64, v94, v98, v64
	v_max_f32_e32 v64, 0xda24260, v64
	v_cmp_gt_f32_e32 vcc, s93, v64
	v_add_f32_e32 v92, 1.0, v92
	v_rcp_f32_e32 v92, v92
	v_cndmask_b32_e64 v94, 0, 32, vcc
	v_ldexp_f32 v64, v64, v94
	v_log_f32_e32 v64, v64
	s_nop 0
	v_mul_f32_e32 v94, 0x3f317217, v64
	v_fma_f32 v94, v64, s95, -v94
	v_fmac_f32_e32 v94, 0x3377d1cf, v64
	v_fmac_f32_e32 v94, 0x3f317217, v64
	v_cmp_lt_f32_e64 s[42:43], |v64|, s62
	s_nop 1
	v_cndmask_b32_e64 v64, v64, v94, s[42:43]
	v_cndmask_b32_e32 v94, 0, v225, vcc
	v_sub_f32_e32 v94, v64, v94
	v_fma_f32 v64, v95, v99, v65
	v_max_f32_e32 v64, 0xda24260, v64
	v_cmp_gt_f32_e32 vcc, s93, v64
	s_nop 1
	v_cndmask_b32_e64 v65, 0, 32, vcc
	v_ldexp_f32 v64, v64, v65
	v_log_f32_e32 v64, v64
	s_nop 0
	v_mul_f32_e32 v65, 0x3f317217, v64
	v_fma_f32 v65, v64, s95, -v65
	v_fmac_f32_e32 v65, 0x3377d1cf, v64
	v_fmac_f32_e32 v65, 0x3f317217, v64
	v_cmp_lt_f32_e64 s[42:43], |v64|, s62
	s_nop 1
	v_cndmask_b32_e64 v64, v64, v65, s[42:43]
	v_cndmask_b32_e32 v65, 0, v225, vcc
	v_sub_f32_e32 v95, v64, v65
	v_mul_f32_e32 v64, 0xbfb8aa3b, v82
	v_exp_f32_e32 v64, v64
	v_mul_f32_e32 v65, 0xbfb8aa3b, v83
	v_exp_f32_e32 v65, v65
	v_add_f32_e32 v64, 1.0, v64
	v_rcp_f32_e32 v96, v64
	v_add_f32_e32 v65, 1.0, v65
	v_rcp_f32_e32 v97, v65
	v_mul_f32_e32 v64, 0x3fb8aa3b, v82
	v_fma_f32 v66, v96, v100, v66
	v_max_f32_e32 v66, 0xda24260, v66
	v_cmp_gt_f32_e32 vcc, s93, v66
	v_fmac_f32_e32 v67, v97, v101
	v_mul_f32_e32 v65, 0x3fb8aa3b, v83
	v_cndmask_b32_e64 v96, 0, 32, vcc
	v_ldexp_f32 v66, v66, v96
	v_log_f32_e32 v66, v66
	v_exp_f32_e32 v64, v64
	v_exp_f32_e32 v65, v65
	v_mul_f32_e32 v96, 0x3f317217, v66
	v_fma_f32 v96, v66, s95, -v96
	v_fmac_f32_e32 v96, 0x3377d1cf, v66
	v_fmac_f32_e32 v96, 0x3f317217, v66
	v_cmp_lt_f32_e64 s[42:43], |v66|, s62
	v_add_f32_e32 v64, 1.0, v64
	v_add_f32_e32 v65, 1.0, v65
	v_cndmask_b32_e64 v66, v66, v96, s[42:43]
	v_cndmask_b32_e32 v96, 0, v225, vcc
	v_sub_f32_e32 v96, v66, v96
	v_max_f32_e32 v66, 0xda24260, v67
	v_cmp_gt_f32_e32 vcc, s93, v66
	v_rcp_f32_e32 v64, v64
	v_rcp_f32_e32 v65, v65
	v_cndmask_b32_e64 v67, 0, 32, vcc
	v_ldexp_f32 v66, v66, v67
	v_log_f32_e32 v66, v66
	v_pk_mul_f32 v[64:65], v[64:65], v[100:101]
	v_mul_f32_e32 v67, 0x3f317217, v66
	v_fma_f32 v67, v66, s95, -v67
	v_fmac_f32_e32 v67, 0x3377d1cf, v66
	v_fmac_f32_e32 v67, 0x3f317217, v66
	v_cmp_lt_f32_e64 s[42:43], |v66|, s62
	s_nop 1
	v_cndmask_b32_e64 v66, v66, v67, s[42:43]
	v_cndmask_b32_e32 v67, 0, v225, vcc
	v_sub_f32_e32 v97, v66, v67
	v_pk_mul_f32 v[66:67], v[92:93], v[98:99]
	global_store_dwordx4 v[80:81], v[68:71], off
	global_store_dwordx4 v[80:81], v[94:97], off offset:16
